# loop-edge: K-loop counter/pointer SALU and exit compare moved ahead of the back-edge barrier in all five GEMM loops
# speedup vs baseline: 1.0013x; 1.0013x over previous
; #define PG8_STAGE(bufoff, gbase, voff) do { _Pragma("unroll") for (int _i = 0; _i < 2; ++_i) \
;         __builtin_amdgcn_global_load_lds((const unsigned*)((const char*)(gbase) + (voff)[_i]), (PG8_LAS unsigned*)(lds + (bufoff) + ldsw + _i * 8192), 16, 0, 0); } while (0)
; #define PG8_LDA(dst, b, h) do { _Pragma("unroll") for (int m = 0; m < 4; ++m) _Pragma("unroll") for (int k = 0; k < 2; ++k) dst[m][k] = *(const PG8_LAS bf16x8*)(lds + PG8_SA(b, h) + aoff + m * 2048 + k * 1024); } while (0)
; #define PG8_LDB(dst, b, h) do { _Pragma("unroll") for (int n = 0; n < 2; ++n) _Pragma("unroll") for (int k = 0; k < 2; ++k) dst[n][k] = *(const PG8_LAS bf16x8*)(lds + PG8_SB(b, h) + boff + n * 2048 + k * 1024); } while (0)
; #define PG8_MMA(ai, bj, At, Bt) do { __builtin_amdgcn_s_setprio(1); _Pragma("unroll") for (int m = 0; m < 4; ++m) _Pragma("unroll") for (int n = 0; n < 2; ++n) _Pragma("unroll") for (int k = 0; k < 2; ++k) \
;         acc[ai][bj][m][n] = __builtin_amdgcn_mfma_f32_16x16x32_bf16(Bt[n][k], At[m][k], acc[ai][bj][m][n], 0, 0, 0); __builtin_amdgcn_s_setprio(0); } while (0)
; #define PG8_WAIT_V(n) asm volatile("s_waitcnt vmcnt(" #n ")" ::: "memory")
; #define PG8_BAR __builtin_amdgcn_s_barrier()
; template <class Epi, class Sched, bool ALIGN_EPI = false, bool SP2 = false>
; __device__ __forceinline__ void gemm_phase(PG8_LAS unsigned char* lds, const Gemm g, const Sched& S, const Epi& E) {
;     ...
;         for (int t = 0; t < nt; t += 2) {
;             const bool last = (t == nt - 2);
;             const char* a1 = cA + (size_t)(t + 1) * kstep;
;             const char* a2 = last ? nA : cA + (size_t)(t + 2) * kstep; const char* b2 = last ? nB : cB + (size_t)(t + 2) * kstep;
;             const char* a3 = a2 + kstep; const char* b3 = b2 + kstep;
;             if (last && has_next) S.a_ready(nxt);
;             if constexpr (SP2) {
;             PG8_LDB(B0, 0, 0); PG8_LDB(B1, 0, 1); PG8_SCHED; PG8_LDA(At, 0, 0); PG8_STAGE(PG8_SA(1, 1), a1 + hstep, voffA);
;             PG8_WAIT_V(8); PG8_WAIT_L(0); PG8_BAR; PG8_MMA(0, 0, At, B0); PG8_MMA(0, 1, At, B1); PG8_BAR; PG8_SCHED;
;             PG8_LDA(At, 0, 1); PG8_STAGE(PG8_SB(0, 0), b2, voffB); PG8_STAGE(PG8_SB(0, 1), b2 + hstep, voffB); PG8_STAGE(PG8_SA(0, 0), a2, voffA);
;             PG8_WAIT_V(8); PG8_WAIT_L(0); PG8_BAR; PG8_MMA(1, 0, At, B0); PG8_MMA(1, 1, At, B1); PG8_BAR; PG8_SCHED;
.LBB0_182:
	v_add_u32_e32 v158, s85, v186
	ds_read_b128 v[178:181], v158
	ds_read_b128 v[192:195], v158 offset:1024
	ds_read_b128 v[196:199], v158 offset:2048
	ds_read_b128 v[202:205], v158 offset:3072
	v_add_u32_e32 v158, s86, v186
	ds_read_b128 v[206:209], v158
	ds_read_b128 v[210:213], v158 offset:1024
	ds_read_b128 v[214:217], v158 offset:2048
	ds_read_b128 v[218:221], v158 offset:3072
	s_add_u32 s68, s64, 0xfff80080
	s_addc_u32 s69, s65, -1
	s_and_b64 s[66:67], s[66:67], exec
	s_cselect_b32 s69, s55, s69
	s_cselect_b32 s68, s94, s68
	s_cselect_b32 s67, s53, s97
	s_cselect_b32 s66, s95, s96
	v_lshl_add_u64 v[166:167], s[64:65], 0, v[142:143]
	s_add_i32 m0, s77, 0xc000
	ds_read_b128 v[222:225], v133
	ds_read_b128 v[226:229], v133 offset:1024
	ds_read_b128 v[230:233], v133 offset:2048
	ds_read_b128 v[234:237], v133 offset:3072
	ds_read_b128 v[238:241], v133 offset:4096
	ds_read_b128 v[242:245], v133 offset:5120
	ds_read_b128 v[246:249], v133 offset:6144
	ds_read_b128 v[250:253], v133 offset:7168
	global_load_lds_dwordx4 v[166:167], off
	v_lshl_add_u64 v[166:167], s[64:65], 0, v[140:141]
	s_add_i32 m0, s77, 0xe000
	s_nop 0
	global_load_lds_dwordx4 v[166:167], off
	s_waitcnt vmcnt(8)
	s_waitcnt lgkmcnt(0)
	s_barrier
	s_setprio 1
	s_waitcnt lgkmcnt(0)
	v_mfma_f32_16x16x32_bf16 v[126:129], v[178:181], v[222:225], v[126:129]
	v_mfma_f32_16x16x32_bf16 v[122:125], v[196:199], v[222:225], v[122:125]
	v_mfma_f32_16x16x32_bf16 v[114:117], v[178:181], v[230:233], v[114:117]
	v_mfma_f32_16x16x32_bf16 v[106:109], v[196:199], v[230:233], v[106:109]
	v_mfma_f32_16x16x32_bf16 v[98:101], v[178:181], v[238:241], v[98:101]
	v_mfma_f32_16x16x32_bf16 v[90:93], v[196:199], v[238:241], v[90:93]
	v_mfma_f32_16x16x32_bf16 v[82:85], v[178:181], v[246:249], v[82:85]
	v_mfma_f32_16x16x32_bf16 v[74:77], v[196:199], v[246:249], v[74:77]
	v_mfma_f32_16x16x32_bf16 v[126:129], v[192:195], v[226:229], v[126:129]
	v_mfma_f32_16x16x32_bf16 v[122:125], v[202:205], v[226:229], v[122:125]
	v_mfma_f32_16x16x32_bf16 v[114:117], v[192:195], v[234:237], v[114:117]
	v_mfma_f32_16x16x32_bf16 v[106:109], v[202:205], v[234:237], v[106:109]
	v_mfma_f32_16x16x32_bf16 v[98:101], v[192:195], v[242:245], v[98:101]
	v_mfma_f32_16x16x32_bf16 v[90:93], v[202:205], v[242:245], v[90:93]
	v_mfma_f32_16x16x32_bf16 v[82:85], v[192:195], v[250:253], v[82:85]
	v_mfma_f32_16x16x32_bf16 v[74:77], v[202:205], v[250:253], v[74:77]
	s_setprio 0
	s_setprio 1
	v_mfma_f32_16x16x32_bf16 v[118:121], v[206:209], v[222:225], v[118:121]
	v_mfma_f32_16x16x32_bf16 v[110:113], v[214:217], v[222:225], v[110:113]
	v_mfma_f32_16x16x32_bf16 v[102:105], v[206:209], v[230:233], v[102:105]
	v_mfma_f32_16x16x32_bf16 v[94:97], v[214:217], v[230:233], v[94:97]
	v_mfma_f32_16x16x32_bf16 v[86:89], v[206:209], v[238:241], v[86:89]
	v_mfma_f32_16x16x32_bf16 v[78:81], v[214:217], v[238:241], v[78:81]
	v_mfma_f32_16x16x32_bf16 v[70:73], v[206:209], v[246:249], v[70:73]
	v_mfma_f32_16x16x32_bf16 v[66:69], v[214:217], v[246:249], v[66:69]
	v_mfma_f32_16x16x32_bf16 v[118:121], v[210:213], v[226:229], v[118:121]
	v_mfma_f32_16x16x32_bf16 v[110:113], v[218:221], v[226:229], v[110:113]
	v_mfma_f32_16x16x32_bf16 v[102:105], v[210:213], v[234:237], v[102:105]
	v_mfma_f32_16x16x32_bf16 v[94:97], v[218:221], v[234:237], v[94:97]
	v_mfma_f32_16x16x32_bf16 v[86:89], v[210:213], v[242:245], v[86:89]
	v_mfma_f32_16x16x32_bf16 v[78:81], v[218:221], v[242:245], v[78:81]
	v_mfma_f32_16x16x32_bf16 v[70:73], v[210:213], v[250:253], v[70:73]
	v_mfma_f32_16x16x32_bf16 v[66:69], v[218:221], v[250:253], v[66:69]
	s_setprio 0
	s_barrier
	s_add_i32 s99, s85, s73
	v_lshl_add_u64 v[166:167], s[66:67], 0, v[148:149]
	s_mov_b32 m0, s99
	ds_read_b128 v[222:225], v133 offset:16384
	ds_read_b128 v[226:229], v133 offset:17408
	ds_read_b128 v[230:233], v133 offset:18432
	ds_read_b128 v[234:237], v133 offset:19456
	ds_read_b128 v[238:241], v133 offset:20480
	ds_read_b128 v[242:245], v133 offset:21504
	ds_read_b128 v[246:249], v133 offset:22528
	ds_read_b128 v[250:253], v133 offset:23552
	global_load_lds_dwordx4 v[166:167], off
	s_add_i32 m0, s99, 0x2000
	s_add_u32 vcc_lo, s66, 0x80000
	v_lshl_add_u64 v[170:171], s[66:67], 0, v[152:153]
	s_addc_u32 vcc_hi, s67, 0
	s_add_i32 s99, s86, s73
	global_load_lds_dwordx4 v[170:171], off
	v_lshl_add_u64 v[174:175], vcc, 0, v[148:149]
	s_mov_b32 m0, s99
	v_lshl_add_u64 v[182:183], s[68:69], 0, v[150:151]
	global_load_lds_dwordx4 v[174:175], off
	v_lshl_add_u64 v[174:175], vcc, 0, v[152:153]
	s_add_i32 m0, s99, 0x2000
	s_nop 0
	global_load_lds_dwordx4 v[174:175], off
	v_lshl_add_u64 v[174:175], s[68:69], 0, v[146:147]
	s_mov_b32 m0, s77
	s_nop 0
	global_load_lds_dwordx4 v[174:175], off
	s_mov_b32 m0, s78
	s_nop 0
	global_load_lds_dwordx4 v[182:183], off
	s_waitcnt vmcnt(8)
	s_waitcnt lgkmcnt(0)
	s_barrier
; #define PG8_STAGE(bufoff, gbase, voff) do { _Pragma("unroll") for (int _i = 0; _i < 2; ++_i) \
;         __builtin_amdgcn_global_load_lds((const unsigned*)((const char*)(gbase) + (voff)[_i]), (PG8_LAS unsigned*)(lds + (bufoff) + ldsw + _i * 8192), 16, 0, 0); } while (0)
; #define PG8_LDA(dst, b, h) do { _Pragma("unroll") for (int m = 0; m < 4; ++m) _Pragma("unroll") for (int k = 0; k < 2; ++k) dst[m][k] = *(const PG8_LAS bf16x8*)(lds + PG8_SA(b, h) + aoff + m * 2048 + k * 1024); } while (0)
; #define PG8_LDB(dst, b, h) do { _Pragma("unroll") for (int n = 0; n < 2; ++n) _Pragma("unroll") for (int k = 0; k < 2; ++k) dst[n][k] = *(const PG8_LAS bf16x8*)(lds + PG8_SB(b, h) + boff + n * 2048 + k * 1024); } while (0)
; #define PG8_MMA(ai, bj, At, Bt) do { __builtin_amdgcn_s_setprio(1); _Pragma("unroll") for (int m = 0; m < 4; ++m) _Pragma("unroll") for (int n = 0; n < 2; ++n) _Pragma("unroll") for (int k = 0; k < 2; ++k) \
;         acc[ai][bj][m][n] = __builtin_amdgcn_mfma_f32_16x16x32_bf16(Bt[n][k], At[m][k], acc[ai][bj][m][n], 0, 0, 0); __builtin_amdgcn_s_setprio(0); } while (0)
; #define PG8_WAIT_V(n) asm volatile("s_waitcnt vmcnt(" #n ")" ::: "memory")
; #define PG8_WAIT_L(n) asm volatile("s_waitcnt lgkmcnt(" #n ")" ::: "memory")
; #define PG8_BAR __builtin_amdgcn_s_barrier()
; #define PG8_SCHED __builtin_amdgcn_sched_barrier(0)
; template <class Epi, class Sched, bool ALIGN_EPI = false, bool SP2 = false>
; __device__ __forceinline__ void gemm_phase(PG8_LAS unsigned char* lds, const Gemm g, const Sched& S, const Epi& E) {
;     ...
;             PG8_WAIT_V(8); PG8_WAIT_L(0); PG8_BAR; PG8_MMA(1, 0, At, B0); PG8_MMA(1, 1, At, B1); PG8_BAR; PG8_SCHED;
;             PG8_LDB(B0, 1, 0); PG8_LDB(B1, 1, 1); PG8_SCHED; PG8_LDA(At, 1, 0); PG8_STAGE(PG8_SA(0, 1), a2 + hstep, voffA);
;             PG8_WAIT_V(8); PG8_WAIT_L(0); PG8_BAR; PG8_MMA(0, 0, At, B0); PG8_MMA(0, 1, At, B1); PG8_BAR; PG8_SCHED;
;             PG8_LDA(At, 1, 1); PG8_STAGE(PG8_SB(1, 0), b3, voffB); PG8_STAGE(PG8_SB(1, 1), b3 + hstep, voffB); PG8_STAGE(PG8_SA(1, 0), a3, voffA);
	s_setprio 1
	s_waitcnt lgkmcnt(0)
	v_mfma_f32_16x16x32_bf16 v[62:65], v[178:181], v[222:225], v[62:65]
	v_mfma_f32_16x16x32_bf16 v[58:61], v[196:199], v[222:225], v[58:61]
	v_mfma_f32_16x16x32_bf16 v[50:53], v[178:181], v[230:233], v[50:53]
	v_mfma_f32_16x16x32_bf16 v[42:45], v[196:199], v[230:233], v[42:45]
	v_mfma_f32_16x16x32_bf16 v[34:37], v[178:181], v[238:241], v[34:37]
	v_mfma_f32_16x16x32_bf16 v[26:29], v[196:199], v[238:241], v[26:29]
	v_mfma_f32_16x16x32_bf16 v[18:21], v[178:181], v[246:249], v[18:21]
	v_mfma_f32_16x16x32_bf16 v[10:13], v[196:199], v[246:249], v[10:13]
	v_mfma_f32_16x16x32_bf16 v[62:65], v[192:195], v[226:229], v[62:65]
	v_mfma_f32_16x16x32_bf16 v[58:61], v[202:205], v[226:229], v[58:61]
	v_mfma_f32_16x16x32_bf16 v[50:53], v[192:195], v[234:237], v[50:53]
	v_mfma_f32_16x16x32_bf16 v[42:45], v[202:205], v[234:237], v[42:45]
	v_mfma_f32_16x16x32_bf16 v[34:37], v[192:195], v[242:245], v[34:37]
	v_mfma_f32_16x16x32_bf16 v[26:29], v[202:205], v[242:245], v[26:29]
	v_mfma_f32_16x16x32_bf16 v[18:21], v[192:195], v[250:253], v[18:21]
	v_mfma_f32_16x16x32_bf16 v[10:13], v[202:205], v[250:253], v[10:13]
	s_setprio 0
	s_setprio 1
	v_mfma_f32_16x16x32_bf16 v[54:57], v[206:209], v[222:225], v[54:57]
	v_mfma_f32_16x16x32_bf16 v[46:49], v[214:217], v[222:225], v[46:49]
	v_mfma_f32_16x16x32_bf16 v[38:41], v[206:209], v[230:233], v[38:41]
	v_mfma_f32_16x16x32_bf16 v[30:33], v[214:217], v[230:233], v[30:33]
	v_mfma_f32_16x16x32_bf16 v[22:25], v[206:209], v[238:241], v[22:25]
	v_mfma_f32_16x16x32_bf16 v[14:17], v[214:217], v[238:241], v[14:17]
	v_mfma_f32_16x16x32_bf16 v[6:9], v[206:209], v[246:249], v[6:9]
	v_mfma_f32_16x16x32_bf16 v[2:5], v[214:217], v[246:249], v[2:5]
	v_mfma_f32_16x16x32_bf16 v[54:57], v[210:213], v[226:229], v[54:57]
	v_mfma_f32_16x16x32_bf16 v[46:49], v[218:221], v[226:229], v[46:49]
	v_mfma_f32_16x16x32_bf16 v[38:41], v[210:213], v[234:237], v[38:41]
	v_mfma_f32_16x16x32_bf16 v[30:33], v[218:221], v[234:237], v[30:33]
	v_mfma_f32_16x16x32_bf16 v[22:25], v[210:213], v[242:245], v[22:25]
	v_mfma_f32_16x16x32_bf16 v[14:17], v[218:221], v[242:245], v[14:17]
	v_mfma_f32_16x16x32_bf16 v[6:9], v[210:213], v[250:253], v[6:9]
	v_mfma_f32_16x16x32_bf16 v[2:5], v[218:221], v[250:253], v[2:5]
	s_setprio 0
	s_barrier
	s_add_i32 s99, 0, 0x18000
	v_add_u32_e32 v158, s99, v186
	s_add_i32 vcc_lo, 0, 0x1c000
	ds_read_b128 v[178:181], v158
	ds_read_b128 v[192:195], v158 offset:1024
	ds_read_b128 v[196:199], v158 offset:2048
	ds_read_b128 v[202:205], v158 offset:3072
	v_add_u32_e32 v158, vcc_lo, v186
	ds_read_b128 v[206:209], v158
	ds_read_b128 v[210:213], v158 offset:1024
	ds_read_b128 v[214:217], v158 offset:2048
	ds_read_b128 v[218:221], v158 offset:3072
	s_add_u32 s68, s68, 0x80000
	s_addc_u32 s69, s69, 0
	s_mov_b32 m0, s79
	v_lshl_add_u64 v[254:255], s[68:69], 0, v[146:147]
	ds_read_b128 v[222:225], v133 offset:32768
	ds_read_b128 v[226:229], v133 offset:33792
	ds_read_b128 v[230:233], v133 offset:34816
	ds_read_b128 v[234:237], v133 offset:35840
	ds_read_b128 v[238:241], v133 offset:36864
	ds_read_b128 v[242:245], v133 offset:37888
	ds_read_b128 v[246:249], v133 offset:38912
	ds_read_b128 v[250:253], v133 offset:39936
	global_load_lds_dwordx4 v[254:255], off
	v_lshl_add_u64 v[254:255], s[68:69], 0, v[150:151]
	s_mov_b32 m0, s80
	s_nop 0
	global_load_lds_dwordx4 v[254:255], off
	s_waitcnt vmcnt(8)
	s_waitcnt lgkmcnt(0)
	s_barrier
	s_setprio 1
	s_waitcnt lgkmcnt(0)
	v_mfma_f32_16x16x32_bf16 v[126:129], v[178:181], v[222:225], v[126:129]
	v_mfma_f32_16x16x32_bf16 v[122:125], v[196:199], v[222:225], v[122:125]
	v_mfma_f32_16x16x32_bf16 v[114:117], v[178:181], v[230:233], v[114:117]
	v_mfma_f32_16x16x32_bf16 v[106:109], v[196:199], v[230:233], v[106:109]
	v_mfma_f32_16x16x32_bf16 v[98:101], v[178:181], v[238:241], v[98:101]
	v_mfma_f32_16x16x32_bf16 v[90:93], v[196:199], v[238:241], v[90:93]
	v_mfma_f32_16x16x32_bf16 v[82:85], v[178:181], v[246:249], v[82:85]
	v_mfma_f32_16x16x32_bf16 v[74:77], v[196:199], v[246:249], v[74:77]
	v_mfma_f32_16x16x32_bf16 v[126:129], v[192:195], v[226:229], v[126:129]
	v_mfma_f32_16x16x32_bf16 v[122:125], v[202:205], v[226:229], v[122:125]
	v_mfma_f32_16x16x32_bf16 v[114:117], v[192:195], v[234:237], v[114:117]
	v_mfma_f32_16x16x32_bf16 v[106:109], v[202:205], v[234:237], v[106:109]
	v_mfma_f32_16x16x32_bf16 v[98:101], v[192:195], v[242:245], v[98:101]
	v_mfma_f32_16x16x32_bf16 v[90:93], v[202:205], v[242:245], v[90:93]
	v_mfma_f32_16x16x32_bf16 v[82:85], v[192:195], v[250:253], v[82:85]
	v_mfma_f32_16x16x32_bf16 v[74:77], v[202:205], v[250:253], v[74:77]
	s_setprio 0
	s_setprio 1
	v_mfma_f32_16x16x32_bf16 v[118:121], v[206:209], v[222:225], v[118:121]
	v_mfma_f32_16x16x32_bf16 v[110:113], v[214:217], v[222:225], v[110:113]
	v_mfma_f32_16x16x32_bf16 v[102:105], v[206:209], v[230:233], v[102:105]
	v_mfma_f32_16x16x32_bf16 v[94:97], v[214:217], v[230:233], v[94:97]
	v_mfma_f32_16x16x32_bf16 v[86:89], v[206:209], v[238:241], v[86:89]
	v_mfma_f32_16x16x32_bf16 v[78:81], v[214:217], v[238:241], v[78:81]
	v_mfma_f32_16x16x32_bf16 v[70:73], v[206:209], v[246:249], v[70:73]
	v_mfma_f32_16x16x32_bf16 v[66:69], v[214:217], v[246:249], v[66:69]
	v_mfma_f32_16x16x32_bf16 v[118:121], v[210:213], v[226:229], v[118:121]
	v_mfma_f32_16x16x32_bf16 v[110:113], v[218:221], v[226:229], v[110:113]
	v_mfma_f32_16x16x32_bf16 v[102:105], v[210:213], v[234:237], v[102:105]
	v_mfma_f32_16x16x32_bf16 v[94:97], v[218:221], v[234:237], v[94:97]
	v_mfma_f32_16x16x32_bf16 v[86:89], v[210:213], v[242:245], v[86:89]
	v_mfma_f32_16x16x32_bf16 v[78:81], v[218:221], v[242:245], v[78:81]
	v_mfma_f32_16x16x32_bf16 v[70:73], v[210:213], v[250:253], v[70:73]
	v_mfma_f32_16x16x32_bf16 v[66:69], v[218:221], v[250:253], v[66:69]
	s_setprio 0
	s_barrier
; #define PG8_STAGE(bufoff, gbase, voff) do { _Pragma("unroll") for (int _i = 0; _i < 2; ++_i) \
;         __builtin_amdgcn_global_load_lds((const unsigned*)((const char*)(gbase) + (voff)[_i]), (PG8_LAS unsigned*)(lds + (bufoff) + ldsw + _i * 8192), 16, 0, 0); } while (0)
; #define PG8_LDA(dst, b, h) do { _Pragma("unroll") for (int m = 0; m < 4; ++m) _Pragma("unroll") for (int k = 0; k < 2; ++k) dst[m][k] = *(const PG8_LAS bf16x8*)(lds + PG8_SA(b, h) + aoff + m * 2048 + k * 1024); } while (0)
; #define PG8_MMA(ai, bj, At, Bt) do { __builtin_amdgcn_s_setprio(1); _Pragma("unroll") for (int m = 0; m < 4; ++m) _Pragma("unroll") for (int n = 0; n < 2; ++n) _Pragma("unroll") for (int k = 0; k < 2; ++k) \
;         acc[ai][bj][m][n] = __builtin_amdgcn_mfma_f32_16x16x32_bf16(Bt[n][k], At[m][k], acc[ai][bj][m][n], 0, 0, 0); __builtin_amdgcn_s_setprio(0); } while (0)
; #define PG8_WAIT_V(n) asm volatile("s_waitcnt vmcnt(" #n ")" ::: "memory")
; #define PG8_WAIT_L(n) asm volatile("s_waitcnt lgkmcnt(" #n ")" ::: "memory")
; #define PG8_BAR __builtin_amdgcn_s_barrier()
; #define PG8_SCHED __builtin_amdgcn_sched_barrier(0)
; template <class Epi, class Sched, bool ALIGN_EPI = false, bool SP2 = false>
; __device__ __forceinline__ void gemm_phase(PG8_LAS unsigned char* lds, const Gemm g, const Sched& S, const Epi& E) {
;     ...
;         for (int t = 0; t < nt; t += 2) {
;     ...
;             PG8_LDA(At, 1, 1); PG8_STAGE(PG8_SB(1, 0), b3, voffB); PG8_STAGE(PG8_SB(1, 1), b3 + hstep, voffB); PG8_STAGE(PG8_SA(1, 0), a3, voffA);
;             PG8_WAIT_V(8); PG8_WAIT_L(0); PG8_BAR; PG8_MMA(1, 0, At, B0); PG8_MMA(1, 1, At, B1); PG8_BAR; PG8_SCHED;
	s_add_i32 s68, s99, s73
	v_lshl_add_u64 v[166:167], v[166:167], 0, s[38:39]
	s_mov_b32 m0, s68
	ds_read_b128 v[222:225], v133 offset:49152
	ds_read_b128 v[226:229], v133 offset:50176
	ds_read_b128 v[230:233], v133 offset:51200
	ds_read_b128 v[234:237], v133 offset:52224
	ds_read_b128 v[238:241], v133 offset:53248
	ds_read_b128 v[242:245], v133 offset:54272
	ds_read_b128 v[246:249], v133 offset:55296
	ds_read_b128 v[250:253], v133 offset:56320
	global_load_lds_dwordx4 v[166:167], off
	s_add_i32 m0, s68, 0x2000
	s_add_u32 s66, s66, 0x80080
	v_lshl_add_u64 v[166:167], v[170:171], 0, s[38:39]
	s_addc_u32 s67, s67, 0
	s_add_i32 s68, vcc_lo, s73
	global_load_lds_dwordx4 v[166:167], off
	v_lshl_add_u64 v[166:167], s[66:67], 0, v[148:149]
	s_mov_b32 m0, s68
	s_nop 0
	global_load_lds_dwordx4 v[166:167], off
	v_lshl_add_u64 v[166:167], s[66:67], 0, v[152:153]
	s_add_i32 m0, s68, 0x2000
	s_nop 0
	global_load_lds_dwordx4 v[166:167], off
	v_lshl_add_u64 v[166:167], v[174:175], 0, s[38:39]
	s_mov_b32 m0, s81
	s_nop 0
	global_load_lds_dwordx4 v[166:167], off
	v_lshl_add_u64 v[166:167], v[182:183], 0, s[38:39]
	s_mov_b32 m0, s82
	s_nop 0
	global_load_lds_dwordx4 v[166:167], off
	s_waitcnt vmcnt(8)
	s_waitcnt lgkmcnt(0)
	s_barrier
	s_setprio 1
	s_waitcnt lgkmcnt(0)
	v_mfma_f32_16x16x32_bf16 v[62:65], v[178:181], v[222:225], v[62:65]
	v_mfma_f32_16x16x32_bf16 v[58:61], v[196:199], v[222:225], v[58:61]
	v_mfma_f32_16x16x32_bf16 v[50:53], v[178:181], v[230:233], v[50:53]
	v_mfma_f32_16x16x32_bf16 v[42:45], v[196:199], v[230:233], v[42:45]
	v_mfma_f32_16x16x32_bf16 v[34:37], v[178:181], v[238:241], v[34:37]
	v_mfma_f32_16x16x32_bf16 v[26:29], v[196:199], v[238:241], v[26:29]
	v_mfma_f32_16x16x32_bf16 v[18:21], v[178:181], v[246:249], v[18:21]
	v_mfma_f32_16x16x32_bf16 v[10:13], v[196:199], v[246:249], v[10:13]
	v_mfma_f32_16x16x32_bf16 v[62:65], v[192:195], v[226:229], v[62:65]
	v_mfma_f32_16x16x32_bf16 v[58:61], v[202:205], v[226:229], v[58:61]
	v_mfma_f32_16x16x32_bf16 v[50:53], v[192:195], v[234:237], v[50:53]
	v_mfma_f32_16x16x32_bf16 v[42:45], v[202:205], v[234:237], v[42:45]
	v_mfma_f32_16x16x32_bf16 v[34:37], v[192:195], v[242:245], v[34:37]
	v_mfma_f32_16x16x32_bf16 v[26:29], v[202:205], v[242:245], v[26:29]
	v_mfma_f32_16x16x32_bf16 v[18:21], v[192:195], v[250:253], v[18:21]
	v_mfma_f32_16x16x32_bf16 v[10:13], v[202:205], v[250:253], v[10:13]
	s_setprio 0
	s_setprio 1
	v_mfma_f32_16x16x32_bf16 v[54:57], v[206:209], v[222:225], v[54:57]
	v_mfma_f32_16x16x32_bf16 v[46:49], v[214:217], v[222:225], v[46:49]
	v_mfma_f32_16x16x32_bf16 v[38:41], v[206:209], v[230:233], v[38:41]
	v_mfma_f32_16x16x32_bf16 v[30:33], v[214:217], v[230:233], v[30:33]
	v_mfma_f32_16x16x32_bf16 v[22:25], v[206:209], v[238:241], v[22:25]
	v_mfma_f32_16x16x32_bf16 v[14:17], v[214:217], v[238:241], v[14:17]
	v_mfma_f32_16x16x32_bf16 v[6:9], v[206:209], v[246:249], v[6:9]
	v_mfma_f32_16x16x32_bf16 v[2:5], v[214:217], v[246:249], v[2:5]
	v_mfma_f32_16x16x32_bf16 v[54:57], v[210:213], v[226:229], v[54:57]
	v_mfma_f32_16x16x32_bf16 v[46:49], v[218:221], v[226:229], v[46:49]
	v_mfma_f32_16x16x32_bf16 v[38:41], v[210:213], v[234:237], v[38:41]
	v_mfma_f32_16x16x32_bf16 v[30:33], v[218:221], v[234:237], v[30:33]
	v_mfma_f32_16x16x32_bf16 v[22:25], v[210:213], v[242:245], v[22:25]
	v_mfma_f32_16x16x32_bf16 v[14:17], v[218:221], v[242:245], v[14:17]
	v_mfma_f32_16x16x32_bf16 v[6:9], v[210:213], v[250:253], v[6:9]
	v_mfma_f32_16x16x32_bf16 v[2:5], v[218:221], v[250:253], v[2:5]
	s_setprio 0
	s_add_i32 s98, s98, 2
	s_add_u32 s96, s96, 0x100
	s_addc_u32 s97, s97, 0
	s_add_u32 s64, s64, 0x100
	s_addc_u32 s65, s65, 0
	s_cmp_gt_u32 s98, 29
	s_barrier
	s_cbranch_scc1 .LBB0_185

; #define PG8_STAGE(bufoff, gbase, voff) do { _Pragma("unroll") for (int _i = 0; _i < 2; ++_i) \
;         __builtin_amdgcn_global_load_lds((const unsigned*)((const char*)(gbase) + (voff)[_i]), (PG8_LAS unsigned*)(lds + (bufoff) + ldsw + _i * 8192), 16, 0, 0); } while (0)
; #define PG8_LDA(dst, b, h) do { _Pragma("unroll") for (int m = 0; m < 4; ++m) _Pragma("unroll") for (int k = 0; k < 2; ++k) dst[m][k] = *(const PG8_LAS bf16x8*)(lds + PG8_SA(b, h) + aoff + m * 2048 + k * 1024); } while (0)
; #define PG8_LDB(dst, b, h) do { _Pragma("unroll") for (int n = 0; n < 2; ++n) _Pragma("unroll") for (int k = 0; k < 2; ++k) dst[n][k] = *(const PG8_LAS bf16x8*)(lds + PG8_SB(b, h) + boff + n * 2048 + k * 1024); } while (0)
; #define PG8_MMA(ai, bj, At, Bt) do { __builtin_amdgcn_s_setprio(1); _Pragma("unroll") for (int m = 0; m < 4; ++m) _Pragma("unroll") for (int n = 0; n < 2; ++n) _Pragma("unroll") for (int k = 0; k < 2; ++k) \
;         acc[ai][bj][m][n] = __builtin_amdgcn_mfma_f32_16x16x32_bf16(Bt[n][k], At[m][k], acc[ai][bj][m][n], 0, 0, 0); __builtin_amdgcn_s_setprio(0); } while (0)
; #define PG8_WAIT_V(n) asm volatile("s_waitcnt vmcnt(" #n ")" ::: "memory")
; #define PG8_BAR __builtin_amdgcn_s_barrier()
; template <class Epi, class Sched, bool ALIGN_EPI = false, bool SP2 = false>
; __device__ __forceinline__ void gemm_phase(PG8_LAS unsigned char* lds, const Gemm g, const Sched& S, const Epi& E) {
;     ...
;         for (int t = 0; t < nt; t += 2) {
;             const bool last = (t == nt - 2);
;             const char* a1 = cA + (size_t)(t + 1) * kstep;
;             const char* a2 = last ? nA : cA + (size_t)(t + 2) * kstep; const char* b2 = last ? nB : cB + (size_t)(t + 2) * kstep;
;             const char* a3 = a2 + kstep; const char* b3 = b2 + kstep;
;             if (last && has_next) S.a_ready(nxt);
;             if constexpr (SP2) {
;             PG8_LDB(B0, 0, 0); PG8_LDB(B1, 0, 1); PG8_SCHED; PG8_LDA(At, 0, 0); PG8_STAGE(PG8_SA(1, 1), a1 + hstep, voffA);
;             PG8_WAIT_V(8); PG8_WAIT_L(0); PG8_BAR; PG8_MMA(0, 0, At, B0); PG8_MMA(0, 1, At, B1); PG8_BAR; PG8_SCHED;
;             PG8_LDA(At, 0, 1); PG8_STAGE(PG8_SB(0, 0), b2, voffB); PG8_STAGE(PG8_SB(0, 1), b2 + hstep, voffB); PG8_STAGE(PG8_SA(0, 0), a2, voffA);
;             PG8_WAIT_V(8); PG8_WAIT_L(0); PG8_BAR; PG8_MMA(1, 0, At, B0); PG8_MMA(1, 1, At, B1); PG8_BAR; PG8_SCHED;
.LBB0_212:
	ds_read_b128 v[130:133], v167
	ds_read_b128 v[134:137], v167 offset:1024
	ds_read_b128 v[138:141], v167 offset:2048
	ds_read_b128 v[142:145], v167 offset:3072
	ds_read_b128 v[170:173], v168
	ds_read_b128 v[174:177], v168 offset:1024
	ds_read_b128 v[178:181], v168 offset:2048
	ds_read_b128 v[182:185], v168 offset:3072
	s_add_u32 s70, s68, 0xfff80080
	s_addc_u32 s71, s69, -1
	s_cmp_eq_u32 s98, 28
	s_cselect_b32 s73, s57, s71
	s_cselect_b32 s72, s94, s70
	s_cselect_b32 s71, s55, s97
	s_cselect_b32 s70, s95, s96
	v_lshl_add_u64 v[162:163], s[68:69], 0, v[156:157]
	s_add_i32 m0, s67, 0xc000
	ds_read_b128 v[186:189], v169
	ds_read_b128 v[190:193], v169 offset:1024
	ds_read_b128 v[194:197], v169 offset:2048
	ds_read_b128 v[202:205], v169 offset:3072
	ds_read_b128 v[206:209], v169 offset:4096
	ds_read_b128 v[210:213], v169 offset:5120
	ds_read_b128 v[214:217], v169 offset:6144
	ds_read_b128 v[218:221], v169 offset:7168
	global_load_lds_dwordx4 v[162:163], off
	v_lshl_add_u64 v[162:163], s[68:69], 0, v[154:155]
	s_add_i32 m0, s67, 0xe000
	s_nop 0
	global_load_lds_dwordx4 v[162:163], off
	s_waitcnt vmcnt(8)
	s_waitcnt lgkmcnt(0)
	s_barrier
	s_setprio 1
	s_waitcnt lgkmcnt(0)
	v_mfma_f32_16x16x32_bf16 v[126:129], v[130:133], v[186:189], v[126:129]
	v_mfma_f32_16x16x32_bf16 v[122:125], v[138:141], v[186:189], v[122:125]
	v_mfma_f32_16x16x32_bf16 v[118:121], v[130:133], v[194:197], v[118:121]
	v_mfma_f32_16x16x32_bf16 v[114:117], v[138:141], v[194:197], v[114:117]
	v_mfma_f32_16x16x32_bf16 v[110:113], v[130:133], v[206:209], v[110:113]
	v_mfma_f32_16x16x32_bf16 v[102:105], v[138:141], v[206:209], v[102:105]
	v_mfma_f32_16x16x32_bf16 v[94:97], v[130:133], v[214:217], v[94:97]
	v_mfma_f32_16x16x32_bf16 v[86:89], v[138:141], v[214:217], v[86:89]
	v_mfma_f32_16x16x32_bf16 v[126:129], v[134:137], v[190:193], v[126:129]
	v_mfma_f32_16x16x32_bf16 v[122:125], v[142:145], v[190:193], v[122:125]
	v_mfma_f32_16x16x32_bf16 v[118:121], v[134:137], v[202:205], v[118:121]
	v_mfma_f32_16x16x32_bf16 v[114:117], v[142:145], v[202:205], v[114:117]
	v_mfma_f32_16x16x32_bf16 v[110:113], v[134:137], v[210:213], v[110:113]
	v_mfma_f32_16x16x32_bf16 v[102:105], v[142:145], v[210:213], v[102:105]
	v_mfma_f32_16x16x32_bf16 v[94:97], v[134:137], v[218:221], v[94:97]
	v_mfma_f32_16x16x32_bf16 v[86:89], v[142:145], v[218:221], v[86:89]
	s_setprio 0
	s_setprio 1
	v_mfma_f32_16x16x32_bf16 v[106:109], v[170:173], v[186:189], v[106:109]
	v_mfma_f32_16x16x32_bf16 v[98:101], v[178:181], v[186:189], v[98:101]
	v_mfma_f32_16x16x32_bf16 v[90:93], v[170:173], v[194:197], v[90:93]
	v_mfma_f32_16x16x32_bf16 v[82:85], v[178:181], v[194:197], v[82:85]
	v_mfma_f32_16x16x32_bf16 v[78:81], v[170:173], v[206:209], v[78:81]
	v_mfma_f32_16x16x32_bf16 v[74:77], v[178:181], v[206:209], v[74:77]
	v_mfma_f32_16x16x32_bf16 v[70:73], v[170:173], v[214:217], v[70:73]
	v_mfma_f32_16x16x32_bf16 v[66:69], v[178:181], v[214:217], v[66:69]
	v_mfma_f32_16x16x32_bf16 v[106:109], v[174:177], v[190:193], v[106:109]
	v_mfma_f32_16x16x32_bf16 v[98:101], v[182:185], v[190:193], v[98:101]
	v_mfma_f32_16x16x32_bf16 v[90:93], v[174:177], v[202:205], v[90:93]
	v_mfma_f32_16x16x32_bf16 v[82:85], v[182:185], v[202:205], v[82:85]
	v_mfma_f32_16x16x32_bf16 v[78:81], v[174:177], v[210:213], v[78:81]
	v_mfma_f32_16x16x32_bf16 v[74:77], v[182:185], v[210:213], v[74:77]
	v_mfma_f32_16x16x32_bf16 v[70:73], v[174:177], v[218:221], v[70:73]
	v_mfma_f32_16x16x32_bf16 v[66:69], v[182:185], v[218:221], v[66:69]
	s_setprio 0
	s_barrier
	s_add_i32 s99, s88, s78
	v_lshl_add_u64 v[162:163], s[70:71], 0, v[148:149]
	s_mov_b32 m0, s99
	ds_read_b128 v[186:189], v169 offset:16384
	ds_read_b128 v[190:193], v169 offset:17408
	ds_read_b128 v[194:197], v169 offset:18432
	ds_read_b128 v[202:205], v169 offset:19456
	ds_read_b128 v[206:209], v169 offset:20480
	ds_read_b128 v[210:213], v169 offset:21504
	ds_read_b128 v[214:217], v169 offset:22528
	ds_read_b128 v[218:221], v169 offset:23552
	global_load_lds_dwordx4 v[162:163], off
	s_add_i32 m0, s99, 0x2000
	s_add_u32 vcc_lo, s70, 0x80000
	v_lshl_add_u64 v[198:199], s[70:71], 0, v[152:153]
	s_addc_u32 vcc_hi, s71, 0
	s_add_i32 s99, s89, s78
	global_load_lds_dwordx4 v[198:199], off
	v_lshl_add_u64 v[222:223], vcc, 0, v[148:149]
	s_mov_b32 m0, s99
	v_lshl_add_u64 v[224:225], s[72:73], 0, v[150:151]
	global_load_lds_dwordx4 v[222:223], off
	v_lshl_add_u64 v[222:223], vcc, 0, v[152:153]
	s_add_i32 m0, s99, 0x2000
	s_nop 0
	global_load_lds_dwordx4 v[222:223], off
	v_lshl_add_u64 v[222:223], s[72:73], 0, v[146:147]
	s_mov_b32 m0, s67
	s_nop 0
	global_load_lds_dwordx4 v[222:223], off
	s_mov_b32 m0, s81
	s_nop 0
	global_load_lds_dwordx4 v[224:225], off
	s_waitcnt vmcnt(8)
	s_waitcnt lgkmcnt(0)
	s_barrier
; #define PG8_STAGE(bufoff, gbase, voff) do { _Pragma("unroll") for (int _i = 0; _i < 2; ++_i) \
;         __builtin_amdgcn_global_load_lds((const unsigned*)((const char*)(gbase) + (voff)[_i]), (PG8_LAS unsigned*)(lds + (bufoff) + ldsw + _i * 8192), 16, 0, 0); } while (0)
; #define PG8_LDA(dst, b, h) do { _Pragma("unroll") for (int m = 0; m < 4; ++m) _Pragma("unroll") for (int k = 0; k < 2; ++k) dst[m][k] = *(const PG8_LAS bf16x8*)(lds + PG8_SA(b, h) + aoff + m * 2048 + k * 1024); } while (0)
; #define PG8_LDB(dst, b, h) do { _Pragma("unroll") for (int n = 0; n < 2; ++n) _Pragma("unroll") for (int k = 0; k < 2; ++k) dst[n][k] = *(const PG8_LAS bf16x8*)(lds + PG8_SB(b, h) + boff + n * 2048 + k * 1024); } while (0)
; #define PG8_MMA(ai, bj, At, Bt) do { __builtin_amdgcn_s_setprio(1); _Pragma("unroll") for (int m = 0; m < 4; ++m) _Pragma("unroll") for (int n = 0; n < 2; ++n) _Pragma("unroll") for (int k = 0; k < 2; ++k) \
;         acc[ai][bj][m][n] = __builtin_amdgcn_mfma_f32_16x16x32_bf16(Bt[n][k], At[m][k], acc[ai][bj][m][n], 0, 0, 0); __builtin_amdgcn_s_setprio(0); } while (0)
; #define PG8_WAIT_V(n) asm volatile("s_waitcnt vmcnt(" #n ")" ::: "memory")
; #define PG8_WAIT_L(n) asm volatile("s_waitcnt lgkmcnt(" #n ")" ::: "memory")
; #define PG8_BAR __builtin_amdgcn_s_barrier()
; #define PG8_SCHED __builtin_amdgcn_sched_barrier(0)
; template <class Epi, class Sched, bool ALIGN_EPI = false, bool SP2 = false>
; __device__ __forceinline__ void gemm_phase(PG8_LAS unsigned char* lds, const Gemm g, const Sched& S, const Epi& E) {
;     ...
;             PG8_WAIT_V(8); PG8_WAIT_L(0); PG8_BAR; PG8_MMA(1, 0, At, B0); PG8_MMA(1, 1, At, B1); PG8_BAR; PG8_SCHED;
;             PG8_LDB(B0, 1, 0); PG8_LDB(B1, 1, 1); PG8_SCHED; PG8_LDA(At, 1, 0); PG8_STAGE(PG8_SA(0, 1), a2 + hstep, voffA);
;             PG8_WAIT_V(8); PG8_WAIT_L(0); PG8_BAR; PG8_MMA(0, 0, At, B0); PG8_MMA(0, 1, At, B1); PG8_BAR; PG8_SCHED;
;             PG8_LDA(At, 1, 1); PG8_STAGE(PG8_SB(1, 0), b3, voffB); PG8_STAGE(PG8_SB(1, 1), b3 + hstep, voffB); PG8_STAGE(PG8_SA(1, 0), a3, voffA);
	s_setprio 1
	s_waitcnt lgkmcnt(0)
	v_mfma_f32_16x16x32_bf16 v[62:65], v[130:133], v[186:189], v[62:65]
	v_mfma_f32_16x16x32_bf16 v[58:61], v[138:141], v[186:189], v[58:61]
	v_mfma_f32_16x16x32_bf16 v[50:53], v[130:133], v[194:197], v[50:53]
	v_mfma_f32_16x16x32_bf16 v[42:45], v[138:141], v[194:197], v[42:45]
	v_mfma_f32_16x16x32_bf16 v[34:37], v[130:133], v[206:209], v[34:37]
	v_mfma_f32_16x16x32_bf16 v[26:29], v[138:141], v[206:209], v[26:29]
	v_mfma_f32_16x16x32_bf16 v[18:21], v[130:133], v[214:217], v[18:21]
	v_mfma_f32_16x16x32_bf16 v[10:13], v[138:141], v[214:217], v[10:13]
	v_mfma_f32_16x16x32_bf16 v[62:65], v[134:137], v[190:193], v[62:65]
	v_mfma_f32_16x16x32_bf16 v[58:61], v[142:145], v[190:193], v[58:61]
	v_mfma_f32_16x16x32_bf16 v[50:53], v[134:137], v[202:205], v[50:53]
	v_mfma_f32_16x16x32_bf16 v[42:45], v[142:145], v[202:205], v[42:45]
	v_mfma_f32_16x16x32_bf16 v[34:37], v[134:137], v[210:213], v[34:37]
	v_mfma_f32_16x16x32_bf16 v[26:29], v[142:145], v[210:213], v[26:29]
	v_mfma_f32_16x16x32_bf16 v[18:21], v[134:137], v[218:221], v[18:21]
	v_mfma_f32_16x16x32_bf16 v[10:13], v[142:145], v[218:221], v[10:13]
	s_setprio 0
	s_setprio 1
	v_mfma_f32_16x16x32_bf16 v[54:57], v[170:173], v[186:189], v[54:57]
	v_mfma_f32_16x16x32_bf16 v[46:49], v[178:181], v[186:189], v[46:49]
	v_mfma_f32_16x16x32_bf16 v[38:41], v[170:173], v[194:197], v[38:41]
	v_mfma_f32_16x16x32_bf16 v[30:33], v[178:181], v[194:197], v[30:33]
	v_mfma_f32_16x16x32_bf16 v[22:25], v[170:173], v[206:209], v[22:25]
	v_mfma_f32_16x16x32_bf16 v[14:17], v[178:181], v[206:209], v[14:17]
	v_mfma_f32_16x16x32_bf16 v[6:9], v[170:173], v[214:217], v[6:9]
	v_mfma_f32_16x16x32_bf16 v[2:5], v[178:181], v[214:217], v[2:5]
	v_mfma_f32_16x16x32_bf16 v[54:57], v[174:177], v[190:193], v[54:57]
	v_mfma_f32_16x16x32_bf16 v[46:49], v[182:185], v[190:193], v[46:49]
	v_mfma_f32_16x16x32_bf16 v[38:41], v[174:177], v[202:205], v[38:41]
	v_mfma_f32_16x16x32_bf16 v[30:33], v[182:185], v[202:205], v[30:33]
	v_mfma_f32_16x16x32_bf16 v[22:25], v[174:177], v[210:213], v[22:25]
	v_mfma_f32_16x16x32_bf16 v[14:17], v[182:185], v[210:213], v[14:17]
	v_mfma_f32_16x16x32_bf16 v[6:9], v[174:177], v[218:221], v[6:9]
	v_mfma_f32_16x16x32_bf16 v[2:5], v[182:185], v[218:221], v[2:5]
	s_setprio 0
	s_barrier
	s_add_i32 s99, 0, 0x18000
	s_add_i32 vcc_lo, 0, 0x1c000
	v_add_u32_e32 v142, s99, v165
	v_add_u32_e32 v182, vcc_lo, v165
	ds_read_b128 v[130:133], v142
	ds_read_b128 v[134:137], v142 offset:1024
	ds_read_b128 v[138:141], v142 offset:2048
	ds_read_b128 v[142:145], v142 offset:3072
	ds_read_b128 v[170:173], v182
	ds_read_b128 v[174:177], v182 offset:1024
	ds_read_b128 v[178:181], v182 offset:2048
	ds_read_b128 v[182:185], v182 offset:3072
	s_add_u32 s72, s72, 0x80000
	s_addc_u32 s73, s73, 0
	s_mov_b32 m0, s82
	v_lshl_add_u64 v[226:227], s[72:73], 0, v[146:147]
	ds_read_b128 v[186:189], v169 offset:32768
	ds_read_b128 v[190:193], v169 offset:33792
	ds_read_b128 v[194:197], v169 offset:34816
	ds_read_b128 v[202:205], v169 offset:35840
	ds_read_b128 v[206:209], v169 offset:36864
	ds_read_b128 v[210:213], v169 offset:37888
	ds_read_b128 v[214:217], v169 offset:38912
	ds_read_b128 v[218:221], v169 offset:39936
	global_load_lds_dwordx4 v[226:227], off
	v_lshl_add_u64 v[226:227], s[72:73], 0, v[150:151]
	s_mov_b32 m0, s83
	s_nop 0
	global_load_lds_dwordx4 v[226:227], off
	s_waitcnt vmcnt(8)
	s_waitcnt lgkmcnt(0)
	s_barrier
	s_setprio 1
	s_waitcnt lgkmcnt(0)
	v_mfma_f32_16x16x32_bf16 v[126:129], v[130:133], v[186:189], v[126:129]
	v_mfma_f32_16x16x32_bf16 v[122:125], v[138:141], v[186:189], v[122:125]
	v_mfma_f32_16x16x32_bf16 v[118:121], v[130:133], v[194:197], v[118:121]
	v_mfma_f32_16x16x32_bf16 v[114:117], v[138:141], v[194:197], v[114:117]
	v_mfma_f32_16x16x32_bf16 v[110:113], v[130:133], v[206:209], v[110:113]
	v_mfma_f32_16x16x32_bf16 v[102:105], v[138:141], v[206:209], v[102:105]
	v_mfma_f32_16x16x32_bf16 v[94:97], v[130:133], v[214:217], v[94:97]
	v_mfma_f32_16x16x32_bf16 v[86:89], v[138:141], v[214:217], v[86:89]
	v_mfma_f32_16x16x32_bf16 v[126:129], v[134:137], v[190:193], v[126:129]
	v_mfma_f32_16x16x32_bf16 v[122:125], v[142:145], v[190:193], v[122:125]
	v_mfma_f32_16x16x32_bf16 v[118:121], v[134:137], v[202:205], v[118:121]
	v_mfma_f32_16x16x32_bf16 v[114:117], v[142:145], v[202:205], v[114:117]
	v_mfma_f32_16x16x32_bf16 v[110:113], v[134:137], v[210:213], v[110:113]
	v_mfma_f32_16x16x32_bf16 v[102:105], v[142:145], v[210:213], v[102:105]
	v_mfma_f32_16x16x32_bf16 v[94:97], v[134:137], v[218:221], v[94:97]
	v_mfma_f32_16x16x32_bf16 v[86:89], v[142:145], v[218:221], v[86:89]
	s_setprio 0
	s_setprio 1
	v_mfma_f32_16x16x32_bf16 v[106:109], v[170:173], v[186:189], v[106:109]
	v_mfma_f32_16x16x32_bf16 v[98:101], v[178:181], v[186:189], v[98:101]
	v_mfma_f32_16x16x32_bf16 v[90:93], v[170:173], v[194:197], v[90:93]
	v_mfma_f32_16x16x32_bf16 v[82:85], v[178:181], v[194:197], v[82:85]
	v_mfma_f32_16x16x32_bf16 v[78:81], v[170:173], v[206:209], v[78:81]
	v_mfma_f32_16x16x32_bf16 v[74:77], v[178:181], v[206:209], v[74:77]
	v_mfma_f32_16x16x32_bf16 v[70:73], v[170:173], v[214:217], v[70:73]
	v_mfma_f32_16x16x32_bf16 v[66:69], v[178:181], v[214:217], v[66:69]
	v_mfma_f32_16x16x32_bf16 v[106:109], v[174:177], v[190:193], v[106:109]
	v_mfma_f32_16x16x32_bf16 v[98:101], v[182:185], v[190:193], v[98:101]
	v_mfma_f32_16x16x32_bf16 v[90:93], v[174:177], v[202:205], v[90:93]
	v_mfma_f32_16x16x32_bf16 v[82:85], v[182:185], v[202:205], v[82:85]
	v_mfma_f32_16x16x32_bf16 v[78:81], v[174:177], v[210:213], v[78:81]
	v_mfma_f32_16x16x32_bf16 v[74:77], v[182:185], v[210:213], v[74:77]
	v_mfma_f32_16x16x32_bf16 v[70:73], v[174:177], v[218:221], v[70:73]
	v_mfma_f32_16x16x32_bf16 v[66:69], v[182:185], v[218:221], v[66:69]
	s_setprio 0
	s_barrier
; #define PG8_STAGE(bufoff, gbase, voff) do { _Pragma("unroll") for (int _i = 0; _i < 2; ++_i) \
;         __builtin_amdgcn_global_load_lds((const unsigned*)((const char*)(gbase) + (voff)[_i]), (PG8_LAS unsigned*)(lds + (bufoff) + ldsw + _i * 8192), 16, 0, 0); } while (0)
; #define PG8_LDA(dst, b, h) do { _Pragma("unroll") for (int m = 0; m < 4; ++m) _Pragma("unroll") for (int k = 0; k < 2; ++k) dst[m][k] = *(const PG8_LAS bf16x8*)(lds + PG8_SA(b, h) + aoff + m * 2048 + k * 1024); } while (0)
; #define PG8_MMA(ai, bj, At, Bt) do { __builtin_amdgcn_s_setprio(1); _Pragma("unroll") for (int m = 0; m < 4; ++m) _Pragma("unroll") for (int n = 0; n < 2; ++n) _Pragma("unroll") for (int k = 0; k < 2; ++k) \
;         acc[ai][bj][m][n] = __builtin_amdgcn_mfma_f32_16x16x32_bf16(Bt[n][k], At[m][k], acc[ai][bj][m][n], 0, 0, 0); __builtin_amdgcn_s_setprio(0); } while (0)
; #define PG8_WAIT_V(n) asm volatile("s_waitcnt vmcnt(" #n ")" ::: "memory")
; #define PG8_WAIT_L(n) asm volatile("s_waitcnt lgkmcnt(" #n ")" ::: "memory")
; #define PG8_BAR __builtin_amdgcn_s_barrier()
; #define PG8_SCHED __builtin_amdgcn_sched_barrier(0)
; template <class Epi, class Sched, bool ALIGN_EPI = false, bool SP2 = false>
; __device__ __forceinline__ void gemm_phase(PG8_LAS unsigned char* lds, const Gemm g, const Sched& S, const Epi& E) {
;     ...
;             PG8_LDA(At, 1, 1); PG8_STAGE(PG8_SB(1, 0), b3, voffB); PG8_STAGE(PG8_SB(1, 1), b3 + hstep, voffB); PG8_STAGE(PG8_SA(1, 0), a3, voffA);
;             PG8_WAIT_V(8); PG8_WAIT_L(0); PG8_BAR; PG8_MMA(1, 0, At, B0); PG8_MMA(1, 1, At, B1); PG8_BAR; PG8_SCHED;
;     ...
;         if constexpr (ALIGN_EPI) { if (wr == 0) PG8_BAR; }
	s_add_i32 s72, s99, s78
	v_lshl_add_u64 v[162:163], v[162:163], 0, s[36:37]
	s_mov_b32 m0, s72
	ds_read_b128 v[186:189], v169 offset:49152
	ds_read_b128 v[190:193], v169 offset:50176
	ds_read_b128 v[194:197], v169 offset:51200
	ds_read_b128 v[202:205], v169 offset:52224
	ds_read_b128 v[206:209], v169 offset:53248
	ds_read_b128 v[210:213], v169 offset:54272
	ds_read_b128 v[214:217], v169 offset:55296
	ds_read_b128 v[218:221], v169 offset:56320
	global_load_lds_dwordx4 v[162:163], off
	s_add_i32 m0, s72, 0x2000
	s_add_u32 s70, s70, 0x80080
	v_lshl_add_u64 v[162:163], v[198:199], 0, s[36:37]
	s_addc_u32 s71, s71, 0
	s_add_i32 s72, vcc_lo, s78
	global_load_lds_dwordx4 v[162:163], off
	v_lshl_add_u64 v[162:163], s[70:71], 0, v[148:149]
	s_mov_b32 m0, s72
	s_nop 0
	global_load_lds_dwordx4 v[162:163], off
	v_lshl_add_u64 v[162:163], s[70:71], 0, v[152:153]
	s_add_i32 m0, s72, 0x2000
	s_nop 0
	global_load_lds_dwordx4 v[162:163], off
	v_lshl_add_u64 v[162:163], v[222:223], 0, s[36:37]
	s_mov_b32 m0, s85
	s_nop 0
	global_load_lds_dwordx4 v[162:163], off
	v_lshl_add_u64 v[162:163], v[224:225], 0, s[36:37]
	s_mov_b32 m0, s86
	s_nop 0
	global_load_lds_dwordx4 v[162:163], off
	s_waitcnt vmcnt(8)
	s_waitcnt lgkmcnt(0)
	s_barrier
	s_setprio 1
	s_waitcnt lgkmcnt(0)
	v_mfma_f32_16x16x32_bf16 v[62:65], v[130:133], v[186:189], v[62:65]
	v_mfma_f32_16x16x32_bf16 v[58:61], v[138:141], v[186:189], v[58:61]
	v_mfma_f32_16x16x32_bf16 v[50:53], v[130:133], v[194:197], v[50:53]
	v_mfma_f32_16x16x32_bf16 v[42:45], v[138:141], v[194:197], v[42:45]
	v_mfma_f32_16x16x32_bf16 v[34:37], v[130:133], v[206:209], v[34:37]
	v_mfma_f32_16x16x32_bf16 v[26:29], v[138:141], v[206:209], v[26:29]
	v_mfma_f32_16x16x32_bf16 v[18:21], v[130:133], v[214:217], v[18:21]
	v_mfma_f32_16x16x32_bf16 v[10:13], v[138:141], v[214:217], v[10:13]
	v_mfma_f32_16x16x32_bf16 v[62:65], v[134:137], v[190:193], v[62:65]
	v_mfma_f32_16x16x32_bf16 v[58:61], v[142:145], v[190:193], v[58:61]
	v_mfma_f32_16x16x32_bf16 v[50:53], v[134:137], v[202:205], v[50:53]
	v_mfma_f32_16x16x32_bf16 v[42:45], v[142:145], v[202:205], v[42:45]
	v_mfma_f32_16x16x32_bf16 v[34:37], v[134:137], v[210:213], v[34:37]
	v_mfma_f32_16x16x32_bf16 v[26:29], v[142:145], v[210:213], v[26:29]
	v_mfma_f32_16x16x32_bf16 v[18:21], v[134:137], v[218:221], v[18:21]
	v_mfma_f32_16x16x32_bf16 v[10:13], v[142:145], v[218:221], v[10:13]
	s_setprio 0
	s_setprio 1
	v_mfma_f32_16x16x32_bf16 v[54:57], v[170:173], v[186:189], v[54:57]
	v_mfma_f32_16x16x32_bf16 v[46:49], v[178:181], v[186:189], v[46:49]
	v_mfma_f32_16x16x32_bf16 v[38:41], v[170:173], v[194:197], v[38:41]
	v_mfma_f32_16x16x32_bf16 v[30:33], v[178:181], v[194:197], v[30:33]
	v_mfma_f32_16x16x32_bf16 v[22:25], v[170:173], v[206:209], v[22:25]
	v_mfma_f32_16x16x32_bf16 v[14:17], v[178:181], v[206:209], v[14:17]
	v_mfma_f32_16x16x32_bf16 v[6:9], v[170:173], v[214:217], v[6:9]
	v_mfma_f32_16x16x32_bf16 v[2:5], v[178:181], v[214:217], v[2:5]
	v_mfma_f32_16x16x32_bf16 v[54:57], v[174:177], v[190:193], v[54:57]
	v_mfma_f32_16x16x32_bf16 v[46:49], v[182:185], v[190:193], v[46:49]
	v_mfma_f32_16x16x32_bf16 v[38:41], v[174:177], v[202:205], v[38:41]
	v_mfma_f32_16x16x32_bf16 v[30:33], v[182:185], v[202:205], v[30:33]
	v_mfma_f32_16x16x32_bf16 v[22:25], v[174:177], v[210:213], v[22:25]
	v_mfma_f32_16x16x32_bf16 v[14:17], v[182:185], v[210:213], v[14:17]
	v_mfma_f32_16x16x32_bf16 v[6:9], v[174:177], v[218:221], v[6:9]
	v_mfma_f32_16x16x32_bf16 v[2:5], v[182:185], v[218:221], v[2:5]
	s_setprio 0
	s_add_i32 s98, s98, 2
	s_add_u32 s96, s96, 0x100
	s_addc_u32 s97, s97, 0
	s_add_u32 s68, s68, 0x100
	s_addc_u32 s69, s69, 0
	s_cmp_gt_u32 s98, 29
	s_barrier
	s_cbranch_scc0 .LBB0_212
	s_and_b64 vcc, exec, s[38:39]
	s_cbranch_vccz .LBB0_215
	s_barrier

; #define PG8_STAGE(bufoff, gbase, voff) do { _Pragma("unroll") for (int _i = 0; _i < 2; ++_i) \
;         __builtin_amdgcn_global_load_lds((const unsigned*)((const char*)(gbase) + (voff)[_i]), (PG8_LAS unsigned*)(lds + (bufoff) + ldsw + _i * 8192), 16, 0, 0); } while (0)
; #define PG8_LDA(dst, b, h) do { _Pragma("unroll") for (int m = 0; m < 4; ++m) _Pragma("unroll") for (int k = 0; k < 2; ++k) dst[m][k] = *(const PG8_LAS bf16x8*)(lds + PG8_SA(b, h) + aoff + m * 2048 + k * 1024); } while (0)
; #define PG8_LDB(dst, b, h) do { _Pragma("unroll") for (int n = 0; n < 2; ++n) _Pragma("unroll") for (int k = 0; k < 2; ++k) dst[n][k] = *(const PG8_LAS bf16x8*)(lds + PG8_SB(b, h) + boff + n * 2048 + k * 1024); } while (0)
; #define PG8_MMA(ai, bj, At, Bt) do { __builtin_amdgcn_s_setprio(1); _Pragma("unroll") for (int m = 0; m < 4; ++m) _Pragma("unroll") for (int n = 0; n < 2; ++n) _Pragma("unroll") for (int k = 0; k < 2; ++k) \
;         acc[ai][bj][m][n] = __builtin_amdgcn_mfma_f32_16x16x32_bf16(Bt[n][k], At[m][k], acc[ai][bj][m][n], 0, 0, 0); __builtin_amdgcn_s_setprio(0); } while (0)
; #define PG8_WAIT_V(n) asm volatile("s_waitcnt vmcnt(" #n ")" ::: "memory")
; #define PG8_BAR __builtin_amdgcn_s_barrier()
; template <class Epi, class Sched, bool ALIGN_EPI = false, bool SP2 = false>
; __device__ __forceinline__ void gemm_phase(PG8_LAS unsigned char* lds, const Gemm g, const Sched& S, const Epi& E) {
;     ...
;         for (int t = 0; t < nt; t += 2) {
;             const bool last = (t == nt - 2);
;             const char* a1 = cA + (size_t)(t + 1) * kstep;
;             const char* a2 = last ? nA : cA + (size_t)(t + 2) * kstep; const char* b2 = last ? nB : cB + (size_t)(t + 2) * kstep;
;             const char* a3 = a2 + kstep; const char* b3 = b2 + kstep;
;             if (last && has_next) S.a_ready(nxt);
;             if constexpr (SP2) {
;             PG8_LDB(B0, 0, 0); PG8_LDB(B1, 0, 1); PG8_SCHED; PG8_LDA(At, 0, 0); PG8_STAGE(PG8_SA(1, 1), a1 + hstep, voffA);
;             PG8_WAIT_V(8); PG8_WAIT_L(0); PG8_BAR; PG8_MMA(0, 0, At, B0); PG8_MMA(0, 1, At, B1); PG8_BAR; PG8_SCHED;
;             PG8_LDA(At, 0, 1); PG8_STAGE(PG8_SB(0, 0), b2, voffB); PG8_STAGE(PG8_SB(0, 1), b2 + hstep, voffB); PG8_STAGE(PG8_SA(0, 0), a2, voffA);
;             PG8_WAIT_V(8); PG8_WAIT_L(0); PG8_BAR; PG8_MMA(1, 0, At, B0); PG8_MMA(1, 1, At, B1); PG8_BAR; PG8_SCHED;
.LBB0_517:
	ds_read_b128 v[146:149], v155
	ds_read_b128 v[160:163], v155 offset:1024
	ds_read_b128 v[164:167], v155 offset:2048
	ds_read_b128 v[168:171], v155 offset:3072
	ds_read_b128 v[172:175], v156
	ds_read_b128 v[176:179], v156 offset:1024
	ds_read_b128 v[180:183], v156 offset:2048
	ds_read_b128 v[184:187], v156 offset:3072
	s_add_u32 s52, s50, 0xfff80080
	s_addc_u32 s53, s51, -1
	s_cmp_eq_u32 s78, 28
	s_cselect_b32 s55, s13, s53
	s_cselect_b32 s54, s43, s52
	s_cselect_b32 s53, s41, s77
	s_cselect_b32 s52, s49, s76
	v_lshl_add_u64 v[222:223], s[50:51], 0, v[140:141]
	s_add_i32 m0, s64, 0xc000
	ds_read_b128 v[188:191], v157
	ds_read_b128 v[192:195], v157 offset:1024
	ds_read_b128 v[196:199], v157 offset:2048
	ds_read_b128 v[202:205], v157 offset:3072
	ds_read_b128 v[206:209], v157 offset:4096
	ds_read_b128 v[210:213], v157 offset:5120
	ds_read_b128 v[214:217], v157 offset:6144
	ds_read_b128 v[218:221], v157 offset:7168
	global_load_lds_dwordx4 v[222:223], off
	v_lshl_add_u64 v[222:223], s[50:51], 0, v[138:139]
	s_add_i32 m0, s64, 0xe000
	s_nop 0
	global_load_lds_dwordx4 v[222:223], off
	s_waitcnt vmcnt(8)
	s_waitcnt lgkmcnt(0)
	s_barrier
	s_setprio 1
	s_waitcnt lgkmcnt(0)
	v_mfma_f32_16x16x32_bf16 v[126:129], v[146:149], v[188:191], v[126:129]
	v_mfma_f32_16x16x32_bf16 v[122:125], v[164:167], v[188:191], v[122:125]
	v_mfma_f32_16x16x32_bf16 v[110:113], v[146:149], v[196:199], v[110:113]
	v_mfma_f32_16x16x32_bf16 v[106:109], v[164:167], v[196:199], v[106:109]
	v_mfma_f32_16x16x32_bf16 v[94:97], v[146:149], v[206:209], v[94:97]
	v_mfma_f32_16x16x32_bf16 v[90:93], v[164:167], v[206:209], v[90:93]
	v_mfma_f32_16x16x32_bf16 v[78:81], v[146:149], v[214:217], v[78:81]
	v_mfma_f32_16x16x32_bf16 v[74:77], v[164:167], v[214:217], v[74:77]
	v_mfma_f32_16x16x32_bf16 v[126:129], v[160:163], v[192:195], v[126:129]
	v_mfma_f32_16x16x32_bf16 v[122:125], v[168:171], v[192:195], v[122:125]
	v_mfma_f32_16x16x32_bf16 v[110:113], v[160:163], v[202:205], v[110:113]
	v_mfma_f32_16x16x32_bf16 v[106:109], v[168:171], v[202:205], v[106:109]
	v_mfma_f32_16x16x32_bf16 v[94:97], v[160:163], v[210:213], v[94:97]
	v_mfma_f32_16x16x32_bf16 v[90:93], v[168:171], v[210:213], v[90:93]
	v_mfma_f32_16x16x32_bf16 v[78:81], v[160:163], v[218:221], v[78:81]
	v_mfma_f32_16x16x32_bf16 v[74:77], v[168:171], v[218:221], v[74:77]
	s_setprio 0
	s_setprio 1
	v_mfma_f32_16x16x32_bf16 v[118:121], v[172:175], v[188:191], v[118:121]
	v_mfma_f32_16x16x32_bf16 v[114:117], v[180:183], v[188:191], v[114:117]
	v_mfma_f32_16x16x32_bf16 v[102:105], v[172:175], v[196:199], v[102:105]
	v_mfma_f32_16x16x32_bf16 v[98:101], v[180:183], v[196:199], v[98:101]
	v_mfma_f32_16x16x32_bf16 v[86:89], v[172:175], v[206:209], v[86:89]
	v_mfma_f32_16x16x32_bf16 v[82:85], v[180:183], v[206:209], v[82:85]
	v_mfma_f32_16x16x32_bf16 v[70:73], v[172:175], v[214:217], v[70:73]
	v_mfma_f32_16x16x32_bf16 v[66:69], v[180:183], v[214:217], v[66:69]
	v_mfma_f32_16x16x32_bf16 v[118:121], v[176:179], v[192:195], v[118:121]
	v_mfma_f32_16x16x32_bf16 v[114:117], v[184:187], v[192:195], v[114:117]
	v_mfma_f32_16x16x32_bf16 v[102:105], v[176:179], v[202:205], v[102:105]
	v_mfma_f32_16x16x32_bf16 v[98:101], v[184:187], v[202:205], v[98:101]
	v_mfma_f32_16x16x32_bf16 v[86:89], v[176:179], v[210:213], v[86:89]
	v_mfma_f32_16x16x32_bf16 v[82:85], v[184:187], v[210:213], v[82:85]
	v_mfma_f32_16x16x32_bf16 v[70:73], v[176:179], v[218:221], v[70:73]
	v_mfma_f32_16x16x32_bf16 v[66:69], v[184:187], v[218:221], v[66:69]
	s_setprio 0
	s_barrier
	s_add_i32 s79, s73, s63
	v_lshl_add_u64 v[222:223], s[52:53], 0, v[132:133]
	s_mov_b32 m0, s79
	ds_read_b128 v[188:191], v157 offset:16384
	ds_read_b128 v[192:195], v157 offset:17408
	ds_read_b128 v[196:199], v157 offset:18432
	ds_read_b128 v[202:205], v157 offset:19456
	ds_read_b128 v[206:209], v157 offset:20480
	ds_read_b128 v[210:213], v157 offset:21504
	ds_read_b128 v[214:217], v157 offset:22528
	ds_read_b128 v[218:221], v157 offset:23552
	global_load_lds_dwordx4 v[222:223], off
	s_add_i32 m0, s79, 0x2000
	s_add_u32 s80, s52, 0x80000
	v_lshl_add_u64 v[224:225], s[52:53], 0, v[136:137]
	s_addc_u32 s81, s53, 0
	s_add_i32 s79, s75, s63
	global_load_lds_dwordx4 v[224:225], off
	v_lshl_add_u64 v[226:227], s[80:81], 0, v[132:133]
	s_mov_b32 m0, s79
	v_lshl_add_u64 v[228:229], s[54:55], 0, v[134:135]
	global_load_lds_dwordx4 v[226:227], off
	v_lshl_add_u64 v[226:227], s[80:81], 0, v[136:137]
	s_add_i32 m0, s79, 0x2000
	s_nop 0
	global_load_lds_dwordx4 v[226:227], off
	v_lshl_add_u64 v[226:227], s[54:55], 0, v[130:131]
	s_mov_b32 m0, s64
	s_nop 0
	global_load_lds_dwordx4 v[226:227], off
	s_mov_b32 m0, s65
	s_nop 0
	global_load_lds_dwordx4 v[228:229], off
	s_waitcnt vmcnt(8)
	s_waitcnt lgkmcnt(0)
	s_barrier
; #define PG8_STAGE(bufoff, gbase, voff) do { _Pragma("unroll") for (int _i = 0; _i < 2; ++_i) \
;         __builtin_amdgcn_global_load_lds((const unsigned*)((const char*)(gbase) + (voff)[_i]), (PG8_LAS unsigned*)(lds + (bufoff) + ldsw + _i * 8192), 16, 0, 0); } while (0)
; #define PG8_LDA(dst, b, h) do { _Pragma("unroll") for (int m = 0; m < 4; ++m) _Pragma("unroll") for (int k = 0; k < 2; ++k) dst[m][k] = *(const PG8_LAS bf16x8*)(lds + PG8_SA(b, h) + aoff + m * 2048 + k * 1024); } while (0)
; #define PG8_LDB(dst, b, h) do { _Pragma("unroll") for (int n = 0; n < 2; ++n) _Pragma("unroll") for (int k = 0; k < 2; ++k) dst[n][k] = *(const PG8_LAS bf16x8*)(lds + PG8_SB(b, h) + boff + n * 2048 + k * 1024); } while (0)
; #define PG8_MMA(ai, bj, At, Bt) do { __builtin_amdgcn_s_setprio(1); _Pragma("unroll") for (int m = 0; m < 4; ++m) _Pragma("unroll") for (int n = 0; n < 2; ++n) _Pragma("unroll") for (int k = 0; k < 2; ++k) \
;         acc[ai][bj][m][n] = __builtin_amdgcn_mfma_f32_16x16x32_bf16(Bt[n][k], At[m][k], acc[ai][bj][m][n], 0, 0, 0); __builtin_amdgcn_s_setprio(0); } while (0)
; #define PG8_WAIT_V(n) asm volatile("s_waitcnt vmcnt(" #n ")" ::: "memory")
; #define PG8_WAIT_L(n) asm volatile("s_waitcnt lgkmcnt(" #n ")" ::: "memory")
; #define PG8_BAR __builtin_amdgcn_s_barrier()
; #define PG8_SCHED __builtin_amdgcn_sched_barrier(0)
; template <class Epi, class Sched, bool ALIGN_EPI = false, bool SP2 = false>
; __device__ __forceinline__ void gemm_phase(PG8_LAS unsigned char* lds, const Gemm g, const Sched& S, const Epi& E) {
;     ...
;             PG8_WAIT_V(8); PG8_WAIT_L(0); PG8_BAR; PG8_MMA(1, 0, At, B0); PG8_MMA(1, 1, At, B1); PG8_BAR; PG8_SCHED;
;             PG8_LDB(B0, 1, 0); PG8_LDB(B1, 1, 1); PG8_SCHED; PG8_LDA(At, 1, 0); PG8_STAGE(PG8_SA(0, 1), a2 + hstep, voffA);
;             PG8_WAIT_V(8); PG8_WAIT_L(0); PG8_BAR; PG8_MMA(0, 0, At, B0); PG8_MMA(0, 1, At, B1); PG8_BAR; PG8_SCHED;
;             PG8_LDA(At, 1, 1); PG8_STAGE(PG8_SB(1, 0), b3, voffB); PG8_STAGE(PG8_SB(1, 1), b3 + hstep, voffB); PG8_STAGE(PG8_SA(1, 0), a3, voffA);
	s_setprio 1
	s_waitcnt lgkmcnt(0)
	v_mfma_f32_16x16x32_bf16 v[62:65], v[146:149], v[188:191], v[62:65]
	v_mfma_f32_16x16x32_bf16 v[58:61], v[164:167], v[188:191], v[58:61]
	v_mfma_f32_16x16x32_bf16 v[46:49], v[146:149], v[196:199], v[46:49]
	v_mfma_f32_16x16x32_bf16 v[42:45], v[164:167], v[196:199], v[42:45]
	v_mfma_f32_16x16x32_bf16 v[30:33], v[146:149], v[206:209], v[30:33]
	v_mfma_f32_16x16x32_bf16 v[26:29], v[164:167], v[206:209], v[26:29]
	v_mfma_f32_16x16x32_bf16 v[14:17], v[146:149], v[214:217], v[14:17]
	v_mfma_f32_16x16x32_bf16 v[10:13], v[164:167], v[214:217], v[10:13]
	v_mfma_f32_16x16x32_bf16 v[62:65], v[160:163], v[192:195], v[62:65]
	v_mfma_f32_16x16x32_bf16 v[58:61], v[168:171], v[192:195], v[58:61]
	v_mfma_f32_16x16x32_bf16 v[46:49], v[160:163], v[202:205], v[46:49]
	v_mfma_f32_16x16x32_bf16 v[42:45], v[168:171], v[202:205], v[42:45]
	v_mfma_f32_16x16x32_bf16 v[30:33], v[160:163], v[210:213], v[30:33]
	v_mfma_f32_16x16x32_bf16 v[26:29], v[168:171], v[210:213], v[26:29]
	v_mfma_f32_16x16x32_bf16 v[14:17], v[160:163], v[218:221], v[14:17]
	v_mfma_f32_16x16x32_bf16 v[10:13], v[168:171], v[218:221], v[10:13]
	s_setprio 0
	s_setprio 1
	v_mfma_f32_16x16x32_bf16 v[54:57], v[172:175], v[188:191], v[54:57]
	v_mfma_f32_16x16x32_bf16 v[50:53], v[180:183], v[188:191], v[50:53]
	v_mfma_f32_16x16x32_bf16 v[38:41], v[172:175], v[196:199], v[38:41]
	v_mfma_f32_16x16x32_bf16 v[34:37], v[180:183], v[196:199], v[34:37]
	v_mfma_f32_16x16x32_bf16 v[22:25], v[172:175], v[206:209], v[22:25]
	v_mfma_f32_16x16x32_bf16 v[18:21], v[180:183], v[206:209], v[18:21]
	v_mfma_f32_16x16x32_bf16 v[6:9], v[172:175], v[214:217], v[6:9]
	v_mfma_f32_16x16x32_bf16 v[2:5], v[180:183], v[214:217], v[2:5]
	v_mfma_f32_16x16x32_bf16 v[54:57], v[176:179], v[192:195], v[54:57]
	v_mfma_f32_16x16x32_bf16 v[50:53], v[184:187], v[192:195], v[50:53]
	v_mfma_f32_16x16x32_bf16 v[38:41], v[176:179], v[202:205], v[38:41]
	v_mfma_f32_16x16x32_bf16 v[34:37], v[184:187], v[202:205], v[34:37]
	v_mfma_f32_16x16x32_bf16 v[22:25], v[176:179], v[210:213], v[22:25]
	v_mfma_f32_16x16x32_bf16 v[18:21], v[184:187], v[210:213], v[18:21]
	v_mfma_f32_16x16x32_bf16 v[6:9], v[176:179], v[218:221], v[6:9]
	v_mfma_f32_16x16x32_bf16 v[2:5], v[184:187], v[218:221], v[2:5]
	s_setprio 0
	s_barrier
	s_add_i32 s79, 0, 0x18000
	v_add_u32_e32 v159, s79, v152
	s_add_i32 s80, 0, 0x1c000
	ds_read_b128 v[146:149], v159
	ds_read_b128 v[160:163], v159 offset:1024
	ds_read_b128 v[164:167], v159 offset:2048
	ds_read_b128 v[168:171], v159 offset:3072
	v_add_u32_e32 v159, s80, v152
	ds_read_b128 v[172:175], v159
	ds_read_b128 v[176:179], v159 offset:1024
	ds_read_b128 v[180:183], v159 offset:2048
	ds_read_b128 v[184:187], v159 offset:3072
	s_add_u32 s54, s54, 0x80000
	s_addc_u32 s55, s55, 0
	s_mov_b32 m0, s66
	v_lshl_add_u64 v[230:231], s[54:55], 0, v[130:131]
	ds_read_b128 v[188:191], v157 offset:32768
	ds_read_b128 v[192:195], v157 offset:33792
	ds_read_b128 v[196:199], v157 offset:34816
	ds_read_b128 v[202:205], v157 offset:35840
	ds_read_b128 v[206:209], v157 offset:36864
	ds_read_b128 v[210:213], v157 offset:37888
	ds_read_b128 v[214:217], v157 offset:38912
	ds_read_b128 v[218:221], v157 offset:39936
	global_load_lds_dwordx4 v[230:231], off
	v_lshl_add_u64 v[230:231], s[54:55], 0, v[134:135]
	s_mov_b32 m0, s67
	s_nop 0
	global_load_lds_dwordx4 v[230:231], off
	s_waitcnt vmcnt(8)
	s_waitcnt lgkmcnt(0)
	s_barrier
	s_setprio 1
	s_waitcnt lgkmcnt(0)
	v_mfma_f32_16x16x32_bf16 v[126:129], v[146:149], v[188:191], v[126:129]
	v_mfma_f32_16x16x32_bf16 v[122:125], v[164:167], v[188:191], v[122:125]
	v_mfma_f32_16x16x32_bf16 v[110:113], v[146:149], v[196:199], v[110:113]
	v_mfma_f32_16x16x32_bf16 v[106:109], v[164:167], v[196:199], v[106:109]
	v_mfma_f32_16x16x32_bf16 v[94:97], v[146:149], v[206:209], v[94:97]
	v_mfma_f32_16x16x32_bf16 v[90:93], v[164:167], v[206:209], v[90:93]
	v_mfma_f32_16x16x32_bf16 v[78:81], v[146:149], v[214:217], v[78:81]
	v_mfma_f32_16x16x32_bf16 v[74:77], v[164:167], v[214:217], v[74:77]
	v_mfma_f32_16x16x32_bf16 v[126:129], v[160:163], v[192:195], v[126:129]
	v_mfma_f32_16x16x32_bf16 v[122:125], v[168:171], v[192:195], v[122:125]
	v_mfma_f32_16x16x32_bf16 v[110:113], v[160:163], v[202:205], v[110:113]
	v_mfma_f32_16x16x32_bf16 v[106:109], v[168:171], v[202:205], v[106:109]
	v_mfma_f32_16x16x32_bf16 v[94:97], v[160:163], v[210:213], v[94:97]
	v_mfma_f32_16x16x32_bf16 v[90:93], v[168:171], v[210:213], v[90:93]
	v_mfma_f32_16x16x32_bf16 v[78:81], v[160:163], v[218:221], v[78:81]
	v_mfma_f32_16x16x32_bf16 v[74:77], v[168:171], v[218:221], v[74:77]
	s_setprio 0
	s_setprio 1
	v_mfma_f32_16x16x32_bf16 v[118:121], v[172:175], v[188:191], v[118:121]
	v_mfma_f32_16x16x32_bf16 v[114:117], v[180:183], v[188:191], v[114:117]
	v_mfma_f32_16x16x32_bf16 v[102:105], v[172:175], v[196:199], v[102:105]
	v_mfma_f32_16x16x32_bf16 v[98:101], v[180:183], v[196:199], v[98:101]
	v_mfma_f32_16x16x32_bf16 v[86:89], v[172:175], v[206:209], v[86:89]
	v_mfma_f32_16x16x32_bf16 v[82:85], v[180:183], v[206:209], v[82:85]
	v_mfma_f32_16x16x32_bf16 v[70:73], v[172:175], v[214:217], v[70:73]
	v_mfma_f32_16x16x32_bf16 v[66:69], v[180:183], v[214:217], v[66:69]
	v_mfma_f32_16x16x32_bf16 v[118:121], v[176:179], v[192:195], v[118:121]
	v_mfma_f32_16x16x32_bf16 v[114:117], v[184:187], v[192:195], v[114:117]
	v_mfma_f32_16x16x32_bf16 v[102:105], v[176:179], v[202:205], v[102:105]
	v_mfma_f32_16x16x32_bf16 v[98:101], v[184:187], v[202:205], v[98:101]
	v_mfma_f32_16x16x32_bf16 v[86:89], v[176:179], v[210:213], v[86:89]
	v_mfma_f32_16x16x32_bf16 v[82:85], v[184:187], v[210:213], v[82:85]
	v_mfma_f32_16x16x32_bf16 v[70:73], v[176:179], v[218:221], v[70:73]
	v_mfma_f32_16x16x32_bf16 v[66:69], v[184:187], v[218:221], v[66:69]
	s_setprio 0
	s_barrier
; #define PG8_STAGE(bufoff, gbase, voff) do { _Pragma("unroll") for (int _i = 0; _i < 2; ++_i) \
;         __builtin_amdgcn_global_load_lds((const unsigned*)((const char*)(gbase) + (voff)[_i]), (PG8_LAS unsigned*)(lds + (bufoff) + ldsw + _i * 8192), 16, 0, 0); } while (0)
; #define PG8_LDA(dst, b, h) do { _Pragma("unroll") for (int m = 0; m < 4; ++m) _Pragma("unroll") for (int k = 0; k < 2; ++k) dst[m][k] = *(const PG8_LAS bf16x8*)(lds + PG8_SA(b, h) + aoff + m * 2048 + k * 1024); } while (0)
; #define PG8_MMA(ai, bj, At, Bt) do { __builtin_amdgcn_s_setprio(1); _Pragma("unroll") for (int m = 0; m < 4; ++m) _Pragma("unroll") for (int n = 0; n < 2; ++n) _Pragma("unroll") for (int k = 0; k < 2; ++k) \
;         acc[ai][bj][m][n] = __builtin_amdgcn_mfma_f32_16x16x32_bf16(Bt[n][k], At[m][k], acc[ai][bj][m][n], 0, 0, 0); __builtin_amdgcn_s_setprio(0); } while (0)
; #define PG8_WAIT_V(n) asm volatile("s_waitcnt vmcnt(" #n ")" ::: "memory")
; #define PG8_WAIT_L(n) asm volatile("s_waitcnt lgkmcnt(" #n ")" ::: "memory")
; #define PG8_BAR __builtin_amdgcn_s_barrier()
; #define PG8_SCHED __builtin_amdgcn_sched_barrier(0)
; template <class Epi, class Sched, bool ALIGN_EPI = false, bool SP2 = false>
; __device__ __forceinline__ void gemm_phase(PG8_LAS unsigned char* lds, const Gemm g, const Sched& S, const Epi& E) {
;     ...
;             PG8_LDA(At, 1, 1); PG8_STAGE(PG8_SB(1, 0), b3, voffB); PG8_STAGE(PG8_SB(1, 1), b3 + hstep, voffB); PG8_STAGE(PG8_SA(1, 0), a3, voffA);
;             PG8_WAIT_V(8); PG8_WAIT_L(0); PG8_BAR; PG8_MMA(1, 0, At, B0); PG8_MMA(1, 1, At, B1); PG8_BAR; PG8_SCHED;
;     ...
;         if constexpr (ALIGN_EPI) { if (wr == 0) PG8_BAR; }
	s_add_i32 s54, s79, s63
	v_lshl_add_u64 v[222:223], v[222:223], 0, s[22:23]
	s_mov_b32 m0, s54
	ds_read_b128 v[188:191], v157 offset:49152
	ds_read_b128 v[192:195], v157 offset:50176
	ds_read_b128 v[196:199], v157 offset:51200
	ds_read_b128 v[202:205], v157 offset:52224
	ds_read_b128 v[206:209], v157 offset:53248
	ds_read_b128 v[210:213], v157 offset:54272
	ds_read_b128 v[214:217], v157 offset:55296
	ds_read_b128 v[218:221], v157 offset:56320
	global_load_lds_dwordx4 v[222:223], off
	s_add_i32 m0, s54, 0x2000
	s_add_u32 s52, s52, 0x80080
	v_lshl_add_u64 v[222:223], v[224:225], 0, s[22:23]
	s_addc_u32 s53, s53, 0
	s_add_i32 s54, s80, s63
	global_load_lds_dwordx4 v[222:223], off
	v_lshl_add_u64 v[222:223], s[52:53], 0, v[132:133]
	s_mov_b32 m0, s54
	s_nop 0
	global_load_lds_dwordx4 v[222:223], off
	v_lshl_add_u64 v[222:223], s[52:53], 0, v[136:137]
	s_add_i32 m0, s54, 0x2000
	s_nop 0
	global_load_lds_dwordx4 v[222:223], off
	v_lshl_add_u64 v[222:223], v[226:227], 0, s[22:23]
	s_mov_b32 m0, s69
	s_nop 0
	global_load_lds_dwordx4 v[222:223], off
	v_lshl_add_u64 v[222:223], v[228:229], 0, s[22:23]
	s_mov_b32 m0, s70
	s_nop 0
	global_load_lds_dwordx4 v[222:223], off
	s_waitcnt vmcnt(8)
	s_waitcnt lgkmcnt(0)
	s_barrier
	s_setprio 1
	s_waitcnt lgkmcnt(0)
	v_mfma_f32_16x16x32_bf16 v[62:65], v[146:149], v[188:191], v[62:65]
	v_mfma_f32_16x16x32_bf16 v[58:61], v[164:167], v[188:191], v[58:61]
	v_mfma_f32_16x16x32_bf16 v[46:49], v[146:149], v[196:199], v[46:49]
	v_mfma_f32_16x16x32_bf16 v[42:45], v[164:167], v[196:199], v[42:45]
	v_mfma_f32_16x16x32_bf16 v[30:33], v[146:149], v[206:209], v[30:33]
	v_mfma_f32_16x16x32_bf16 v[26:29], v[164:167], v[206:209], v[26:29]
	v_mfma_f32_16x16x32_bf16 v[14:17], v[146:149], v[214:217], v[14:17]
	v_mfma_f32_16x16x32_bf16 v[10:13], v[164:167], v[214:217], v[10:13]
	v_mfma_f32_16x16x32_bf16 v[62:65], v[160:163], v[192:195], v[62:65]
	v_mfma_f32_16x16x32_bf16 v[58:61], v[168:171], v[192:195], v[58:61]
	v_mfma_f32_16x16x32_bf16 v[46:49], v[160:163], v[202:205], v[46:49]
	v_mfma_f32_16x16x32_bf16 v[42:45], v[168:171], v[202:205], v[42:45]
	v_mfma_f32_16x16x32_bf16 v[30:33], v[160:163], v[210:213], v[30:33]
	v_mfma_f32_16x16x32_bf16 v[26:29], v[168:171], v[210:213], v[26:29]
	v_mfma_f32_16x16x32_bf16 v[14:17], v[160:163], v[218:221], v[14:17]
	v_mfma_f32_16x16x32_bf16 v[10:13], v[168:171], v[218:221], v[10:13]
	s_setprio 0
	s_setprio 1
	v_mfma_f32_16x16x32_bf16 v[54:57], v[172:175], v[188:191], v[54:57]
	v_mfma_f32_16x16x32_bf16 v[50:53], v[180:183], v[188:191], v[50:53]
	v_mfma_f32_16x16x32_bf16 v[38:41], v[172:175], v[196:199], v[38:41]
	v_mfma_f32_16x16x32_bf16 v[34:37], v[180:183], v[196:199], v[34:37]
	v_mfma_f32_16x16x32_bf16 v[22:25], v[172:175], v[206:209], v[22:25]
	v_mfma_f32_16x16x32_bf16 v[18:21], v[180:183], v[206:209], v[18:21]
	v_mfma_f32_16x16x32_bf16 v[6:9], v[172:175], v[214:217], v[6:9]
	v_mfma_f32_16x16x32_bf16 v[2:5], v[180:183], v[214:217], v[2:5]
	v_mfma_f32_16x16x32_bf16 v[54:57], v[176:179], v[192:195], v[54:57]
	v_mfma_f32_16x16x32_bf16 v[50:53], v[184:187], v[192:195], v[50:53]
	v_mfma_f32_16x16x32_bf16 v[38:41], v[176:179], v[202:205], v[38:41]
	v_mfma_f32_16x16x32_bf16 v[34:37], v[184:187], v[202:205], v[34:37]
	v_mfma_f32_16x16x32_bf16 v[22:25], v[176:179], v[210:213], v[22:25]
	v_mfma_f32_16x16x32_bf16 v[18:21], v[184:187], v[210:213], v[18:21]
	v_mfma_f32_16x16x32_bf16 v[6:9], v[176:179], v[218:221], v[6:9]
	v_mfma_f32_16x16x32_bf16 v[2:5], v[184:187], v[218:221], v[2:5]
	s_setprio 0
	s_add_i32 s78, s78, 2
	s_add_u32 s76, s76, 0x100
	s_addc_u32 s77, s77, 0
	s_add_u32 s50, s50, 0x100
	s_addc_u32 s51, s51, 0
	s_cmp_gt_u32 s78, 29
	s_barrier
	s_cbranch_scc0 .LBB0_517
	s_and_b64 vcc, exec, s[24:25]
	s_cbranch_vccz .LBB0_520
	s_barrier

; #define PG8_STAGE(bufoff, gbase, voff) do { _Pragma("unroll") for (int _i = 0; _i < 2; ++_i) \
;         __builtin_amdgcn_global_load_lds((const unsigned*)((const char*)(gbase) + (voff)[_i]), (PG8_LAS unsigned*)(lds + (bufoff) + ldsw + _i * 8192), 16, 0, 0); } while (0)
; #define PG8_LDA(dst, b, h) do { _Pragma("unroll") for (int m = 0; m < 4; ++m) _Pragma("unroll") for (int k = 0; k < 2; ++k) dst[m][k] = *(const PG8_LAS bf16x8*)(lds + PG8_SA(b, h) + aoff + m * 2048 + k * 1024); } while (0)
; #define PG8_LDB(dst, b, h) do { _Pragma("unroll") for (int n = 0; n < 2; ++n) _Pragma("unroll") for (int k = 0; k < 2; ++k) dst[n][k] = *(const PG8_LAS bf16x8*)(lds + PG8_SB(b, h) + boff + n * 2048 + k * 1024); } while (0)
; #define PG8_MMA(ai, bj, At, Bt) do { __builtin_amdgcn_s_setprio(1); _Pragma("unroll") for (int m = 0; m < 4; ++m) _Pragma("unroll") for (int n = 0; n < 2; ++n) _Pragma("unroll") for (int k = 0; k < 2; ++k) \
;         acc[ai][bj][m][n] = __builtin_amdgcn_mfma_f32_16x16x32_bf16(Bt[n][k], At[m][k], acc[ai][bj][m][n], 0, 0, 0); __builtin_amdgcn_s_setprio(0); } while (0)
; #define PG8_WAIT_V(n) asm volatile("s_waitcnt vmcnt(" #n ")" ::: "memory")
; #define PG8_WAIT_L(n) asm volatile("s_waitcnt lgkmcnt(" #n ")" ::: "memory")
; #define PG8_BAR __builtin_amdgcn_s_barrier()
; #define PG8_SCHED __builtin_amdgcn_sched_barrier(0)
; template <class Epi, class Sched, bool ALIGN_EPI = false, bool SP2 = false>
; __device__ __forceinline__ void gemm_phase(PG8_LAS unsigned char* lds, const Gemm g, const Sched& S, const Epi& E) {
;     ...
;             PG8_LDB(B0, 0, 0); PG8_LDB(B1, 0, 1); PG8_SCHED; PG8_LDA(At, 0, 0); PG8_STAGE(PG8_SA(1, 1), a1 + hstep, voffA);
;             PG8_WAIT_V(8); PG8_WAIT_L(0); PG8_BAR; PG8_MMA(0, 0, At, B0); PG8_MMA(0, 1, At, B1); PG8_BAR; PG8_SCHED;
;             PG8_LDA(At, 0, 1); PG8_STAGE(PG8_SB(0, 0), b2, voffB); PG8_STAGE(PG8_SB(0, 1), b2 + hstep, voffB); PG8_STAGE(PG8_SA(0, 0), a2, voffA);
;             PG8_WAIT_V(8); PG8_WAIT_L(0); PG8_BAR; PG8_MMA(1, 0, At, B0); PG8_MMA(1, 1, At, B1); PG8_BAR; PG8_SCHED;
.LBB0_692:
	ds_read_b128 v[162:165], v238
	ds_read_b128 v[166:169], v238 offset:1024
	ds_read_b128 v[170:173], v238 offset:2048
	ds_read_b128 v[174:177], v238 offset:3072
	ds_read_b128 v[178:181], v238 offset:16384
	ds_read_b128 v[182:185], v238 offset:17408
	ds_read_b128 v[186:189], v238 offset:18432
	ds_read_b128 v[190:193], v238 offset:19456
	s_add_u32 s36, s24, 0xfff80080
	s_addc_u32 s37, s25, -1
	s_and_b64 s[26:27], s[26:27], exec
	s_cselect_b32 s37, s17, s37
	s_cselect_b32 s36, s60, s36
	s_cselect_b32 s27, s15, s63
	s_cselect_b32 s26, s61, s62
	s_add_u32 s68, s24, 0xfff80000
	s_addc_u32 s69, s25, -1
	s_mov_b32 m0, s49
	s_nop 0
	global_load_lds_dwordx4 v136, s[68:69]
	s_mov_b32 m0, s50
	s_nop 0
	global_load_lds_dwordx4 v132, s[68:69]
	s_add_i32 m0, s23, 0xc000
	ds_read_b128 v[194:197], v159
	ds_read_b128 v[202:205], v159 offset:1024
	ds_read_b128 v[206:209], v159 offset:2048
	ds_read_b128 v[210:213], v159 offset:3072
	ds_read_b128 v[214:217], v159 offset:4096
	ds_read_b128 v[218:221], v159 offset:5120
	ds_read_b128 v[222:225], v159 offset:6144
	ds_read_b128 v[226:229], v159 offset:7168
	global_load_lds_dwordx4 v144, s[24:25]
	s_add_i32 m0, s23, 0xe000
	s_nop 0
	global_load_lds_dwordx4 v138, s[24:25]
	s_waitcnt vmcnt(8)
	s_waitcnt lgkmcnt(0)
	s_barrier
	s_setprio 1
	s_waitcnt lgkmcnt(0)
	v_mfma_f32_16x16x32_bf16 v[126:129], v[162:165], v[194:197], v[126:129]
	v_mfma_f32_16x16x32_bf16 v[118:121], v[170:173], v[194:197], v[118:121]
	v_mfma_f32_16x16x32_bf16 v[110:113], v[162:165], v[206:209], v[110:113]
	v_mfma_f32_16x16x32_bf16 v[102:105], v[170:173], v[206:209], v[102:105]
	v_mfma_f32_16x16x32_bf16 v[94:97], v[162:165], v[214:217], v[94:97]
	v_mfma_f32_16x16x32_bf16 v[86:89], v[170:173], v[214:217], v[86:89]
	v_mfma_f32_16x16x32_bf16 v[78:81], v[162:165], v[222:225], v[78:81]
	v_mfma_f32_16x16x32_bf16 v[70:73], v[170:173], v[222:225], v[70:73]
	v_mfma_f32_16x16x32_bf16 v[126:129], v[166:169], v[202:205], v[126:129]
	v_mfma_f32_16x16x32_bf16 v[118:121], v[174:177], v[202:205], v[118:121]
	v_mfma_f32_16x16x32_bf16 v[110:113], v[166:169], v[210:213], v[110:113]
	v_mfma_f32_16x16x32_bf16 v[102:105], v[174:177], v[210:213], v[102:105]
	v_mfma_f32_16x16x32_bf16 v[94:97], v[166:169], v[218:221], v[94:97]
	v_mfma_f32_16x16x32_bf16 v[86:89], v[174:177], v[218:221], v[86:89]
	v_mfma_f32_16x16x32_bf16 v[78:81], v[166:169], v[226:229], v[78:81]
	v_mfma_f32_16x16x32_bf16 v[70:73], v[174:177], v[226:229], v[70:73]
	s_setprio 0
	s_setprio 1
	v_mfma_f32_16x16x32_bf16 v[122:125], v[178:181], v[194:197], v[122:125]
	v_mfma_f32_16x16x32_bf16 v[114:117], v[186:189], v[194:197], v[114:117]
	v_mfma_f32_16x16x32_bf16 v[106:109], v[178:181], v[206:209], v[106:109]
	v_mfma_f32_16x16x32_bf16 v[98:101], v[186:189], v[206:209], v[98:101]
	v_mfma_f32_16x16x32_bf16 v[90:93], v[178:181], v[214:217], v[90:93]
	v_mfma_f32_16x16x32_bf16 v[82:85], v[186:189], v[214:217], v[82:85]
	v_mfma_f32_16x16x32_bf16 v[74:77], v[178:181], v[222:225], v[74:77]
	v_mfma_f32_16x16x32_bf16 v[66:69], v[186:189], v[222:225], v[66:69]
	v_mfma_f32_16x16x32_bf16 v[122:125], v[182:185], v[202:205], v[122:125]
	v_mfma_f32_16x16x32_bf16 v[114:117], v[190:193], v[202:205], v[114:117]
	v_mfma_f32_16x16x32_bf16 v[106:109], v[182:185], v[210:213], v[106:109]
	v_mfma_f32_16x16x32_bf16 v[98:101], v[190:193], v[210:213], v[98:101]
	v_mfma_f32_16x16x32_bf16 v[90:93], v[182:185], v[218:221], v[90:93]
	v_mfma_f32_16x16x32_bf16 v[82:85], v[190:193], v[218:221], v[82:85]
	v_mfma_f32_16x16x32_bf16 v[74:77], v[182:185], v[226:229], v[74:77]
	v_mfma_f32_16x16x32_bf16 v[66:69], v[190:193], v[226:229], v[66:69]
	s_setprio 0
	s_barrier
	s_add_i32 s65, s52, s42
	s_mov_b32 m0, s65
	ds_read_b128 v[194:197], v159 offset:16384
	ds_read_b128 v[202:205], v159 offset:17408
	ds_read_b128 v[206:209], v159 offset:18432
	ds_read_b128 v[210:213], v159 offset:19456
	ds_read_b128 v[214:217], v159 offset:20480
	ds_read_b128 v[218:221], v159 offset:21504
	ds_read_b128 v[222:225], v159 offset:22528
	ds_read_b128 v[226:229], v159 offset:23552
	global_load_lds_dwordx4 v134, s[26:27]
	s_add_i32 m0, s65, 0x2000
	s_add_u32 s66, s26, 0x80000
	s_addc_u32 s67, s27, 0
	s_add_i32 s65, s53, s42
	global_load_lds_dwordx4 v130, s[26:27]
	s_mov_b32 m0, s65
	s_nop 0
	global_load_lds_dwordx4 v134, s[66:67]
	s_add_i32 m0, s65, 0x2000
	s_nop 0
	global_load_lds_dwordx4 v130, s[66:67]
	s_waitcnt vmcnt(6)
	s_waitcnt lgkmcnt(0)
	s_barrier
	s_setprio 1
	s_waitcnt lgkmcnt(0)
	v_mfma_f32_16x16x32_bf16 v[62:65], v[162:165], v[194:197], v[62:65]
	v_mfma_f32_16x16x32_bf16 v[54:57], v[170:173], v[194:197], v[54:57]
	v_mfma_f32_16x16x32_bf16 v[46:49], v[162:165], v[206:209], v[46:49]
	v_mfma_f32_16x16x32_bf16 v[38:41], v[170:173], v[206:209], v[38:41]
	v_mfma_f32_16x16x32_bf16 v[30:33], v[162:165], v[214:217], v[30:33]
	v_mfma_f32_16x16x32_bf16 v[22:25], v[170:173], v[214:217], v[22:25]
	v_mfma_f32_16x16x32_bf16 v[14:17], v[162:165], v[222:225], v[14:17]
	v_mfma_f32_16x16x32_bf16 v[6:9], v[170:173], v[222:225], v[6:9]
	v_mfma_f32_16x16x32_bf16 v[62:65], v[166:169], v[202:205], v[62:65]
	v_mfma_f32_16x16x32_bf16 v[54:57], v[174:177], v[202:205], v[54:57]
	v_mfma_f32_16x16x32_bf16 v[46:49], v[166:169], v[210:213], v[46:49]
	v_mfma_f32_16x16x32_bf16 v[38:41], v[174:177], v[210:213], v[38:41]
	v_mfma_f32_16x16x32_bf16 v[30:33], v[166:169], v[218:221], v[30:33]
	v_mfma_f32_16x16x32_bf16 v[22:25], v[174:177], v[218:221], v[22:25]
	v_mfma_f32_16x16x32_bf16 v[14:17], v[166:169], v[226:229], v[14:17]
	v_mfma_f32_16x16x32_bf16 v[6:9], v[174:177], v[226:229], v[6:9]
	s_setprio 0
	s_setprio 1
	v_mfma_f32_16x16x32_bf16 v[58:61], v[178:181], v[194:197], v[58:61]
	v_mfma_f32_16x16x32_bf16 v[50:53], v[186:189], v[194:197], v[50:53]
	v_mfma_f32_16x16x32_bf16 v[42:45], v[178:181], v[206:209], v[42:45]
	v_mfma_f32_16x16x32_bf16 v[34:37], v[186:189], v[206:209], v[34:37]
	v_mfma_f32_16x16x32_bf16 v[26:29], v[178:181], v[214:217], v[26:29]
	v_mfma_f32_16x16x32_bf16 v[18:21], v[186:189], v[214:217], v[18:21]
	v_mfma_f32_16x16x32_bf16 v[10:13], v[178:181], v[222:225], v[10:13]
	v_mfma_f32_16x16x32_bf16 v[2:5], v[186:189], v[222:225], v[2:5]
	v_mfma_f32_16x16x32_bf16 v[58:61], v[182:185], v[202:205], v[58:61]
	v_mfma_f32_16x16x32_bf16 v[50:53], v[190:193], v[202:205], v[50:53]
	v_mfma_f32_16x16x32_bf16 v[42:45], v[182:185], v[210:213], v[42:45]
	v_mfma_f32_16x16x32_bf16 v[34:37], v[190:193], v[210:213], v[34:37]
	v_mfma_f32_16x16x32_bf16 v[26:29], v[182:185], v[218:221], v[26:29]
	v_mfma_f32_16x16x32_bf16 v[18:21], v[190:193], v[218:221], v[18:21]
	v_mfma_f32_16x16x32_bf16 v[10:13], v[182:185], v[226:229], v[10:13]
	v_mfma_f32_16x16x32_bf16 v[2:5], v[190:193], v[226:229], v[2:5]
	s_setprio 0
	s_barrier
; #define PG8_STAGE(bufoff, gbase, voff) do { _Pragma("unroll") for (int _i = 0; _i < 2; ++_i) \
;         __builtin_amdgcn_global_load_lds((const unsigned*)((const char*)(gbase) + (voff)[_i]), (PG8_LAS unsigned*)(lds + (bufoff) + ldsw + _i * 8192), 16, 0, 0); } while (0)
; #define PG8_LDA(dst, b, h) do { _Pragma("unroll") for (int m = 0; m < 4; ++m) _Pragma("unroll") for (int k = 0; k < 2; ++k) dst[m][k] = *(const PG8_LAS bf16x8*)(lds + PG8_SA(b, h) + aoff + m * 2048 + k * 1024); } while (0)
; #define PG8_LDB(dst, b, h) do { _Pragma("unroll") for (int n = 0; n < 2; ++n) _Pragma("unroll") for (int k = 0; k < 2; ++k) dst[n][k] = *(const PG8_LAS bf16x8*)(lds + PG8_SB(b, h) + boff + n * 2048 + k * 1024); } while (0)
; #define PG8_MMA(ai, bj, At, Bt) do { __builtin_amdgcn_s_setprio(1); _Pragma("unroll") for (int m = 0; m < 4; ++m) _Pragma("unroll") for (int n = 0; n < 2; ++n) _Pragma("unroll") for (int k = 0; k < 2; ++k) \
;         acc[ai][bj][m][n] = __builtin_amdgcn_mfma_f32_16x16x32_bf16(Bt[n][k], At[m][k], acc[ai][bj][m][n], 0, 0, 0); __builtin_amdgcn_s_setprio(0); } while (0)
; #define PG8_WAIT_V(n) asm volatile("s_waitcnt vmcnt(" #n ")" ::: "memory")
; #define PG8_WAIT_L(n) asm volatile("s_waitcnt lgkmcnt(" #n ")" ::: "memory")
; #define PG8_BAR __builtin_amdgcn_s_barrier()
; #define PG8_SCHED __builtin_amdgcn_sched_barrier(0)
; template <class Epi, class Sched, bool ALIGN_EPI = false, bool SP2 = false>
; __device__ __forceinline__ void gemm_phase(PG8_LAS unsigned char* lds, const Gemm g, const Sched& S, const Epi& E) {
;     ...
;             PG8_LDB(B0, 1, 0); PG8_LDB(B1, 1, 1); PG8_SCHED; PG8_LDA(At, 1, 0); PG8_STAGE(PG8_SA(0, 1), a2 + hstep, voffA);
;             PG8_WAIT_V(8); PG8_WAIT_L(0); PG8_BAR; PG8_MMA(0, 0, At, B0); PG8_MMA(0, 1, At, B1); PG8_BAR; PG8_SCHED;
;             PG8_LDA(At, 1, 1); PG8_STAGE(PG8_SB(1, 0), b3, voffB); PG8_STAGE(PG8_SB(1, 1), b3 + hstep, voffB); PG8_STAGE(PG8_SA(1, 0), a3, voffA);
;             PG8_WAIT_V(8); PG8_WAIT_L(0); PG8_BAR; PG8_MMA(1, 0, At, B0); PG8_MMA(1, 1, At, B1); PG8_BAR; PG8_SCHED;
	s_add_i32 s65, 0, 0x18000
	s_add_i32 s66, 0, 0x1c000
	ds_read_b128 v[162:165], v238 offset:32768
	ds_read_b128 v[166:169], v238 offset:33792
	ds_read_b128 v[170:173], v238 offset:34816
	ds_read_b128 v[174:177], v238 offset:35840
	ds_read_b128 v[178:181], v238 offset:49152
	ds_read_b128 v[182:185], v238 offset:50176
	ds_read_b128 v[186:189], v238 offset:51200
	ds_read_b128 v[190:193], v238 offset:52224
	s_mov_b32 m0, s23
	s_nop 0
	global_load_lds_dwordx4 v136, s[36:37]
	s_mov_b32 m0, s45
	s_nop 0
	global_load_lds_dwordx4 v132, s[36:37]
	s_add_u32 s36, s36, 0x80000
	s_addc_u32 s37, s37, 0
	s_mov_b32 m0, s46
	ds_read_b128 v[194:197], v159 offset:32768
	ds_read_b128 v[202:205], v159 offset:33792
	ds_read_b128 v[206:209], v159 offset:34816
	ds_read_b128 v[210:213], v159 offset:35840
	ds_read_b128 v[214:217], v159 offset:36864
	ds_read_b128 v[218:221], v159 offset:37888
	ds_read_b128 v[222:225], v159 offset:38912
	ds_read_b128 v[226:229], v159 offset:39936
	global_load_lds_dwordx4 v136, s[36:37]
	s_mov_b32 m0, s47
	s_nop 0
	global_load_lds_dwordx4 v132, s[36:37]
	s_waitcnt vmcnt(8)
	s_waitcnt lgkmcnt(0)
	s_barrier
	s_setprio 1
	s_waitcnt lgkmcnt(0)
	v_mfma_f32_16x16x32_bf16 v[126:129], v[162:165], v[194:197], v[126:129]
	v_mfma_f32_16x16x32_bf16 v[118:121], v[170:173], v[194:197], v[118:121]
	v_mfma_f32_16x16x32_bf16 v[110:113], v[162:165], v[206:209], v[110:113]
	v_mfma_f32_16x16x32_bf16 v[102:105], v[170:173], v[206:209], v[102:105]
	v_mfma_f32_16x16x32_bf16 v[94:97], v[162:165], v[214:217], v[94:97]
	v_mfma_f32_16x16x32_bf16 v[86:89], v[170:173], v[214:217], v[86:89]
	v_mfma_f32_16x16x32_bf16 v[78:81], v[162:165], v[222:225], v[78:81]
	v_mfma_f32_16x16x32_bf16 v[70:73], v[170:173], v[222:225], v[70:73]
	v_mfma_f32_16x16x32_bf16 v[126:129], v[166:169], v[202:205], v[126:129]
	v_mfma_f32_16x16x32_bf16 v[118:121], v[174:177], v[202:205], v[118:121]
	v_mfma_f32_16x16x32_bf16 v[110:113], v[166:169], v[210:213], v[110:113]
	v_mfma_f32_16x16x32_bf16 v[102:105], v[174:177], v[210:213], v[102:105]
	v_mfma_f32_16x16x32_bf16 v[94:97], v[166:169], v[218:221], v[94:97]
	v_mfma_f32_16x16x32_bf16 v[86:89], v[174:177], v[218:221], v[86:89]
	v_mfma_f32_16x16x32_bf16 v[78:81], v[166:169], v[226:229], v[78:81]
	v_mfma_f32_16x16x32_bf16 v[70:73], v[174:177], v[226:229], v[70:73]
	s_setprio 0
	s_setprio 1
	v_mfma_f32_16x16x32_bf16 v[122:125], v[178:181], v[194:197], v[122:125]
	v_mfma_f32_16x16x32_bf16 v[114:117], v[186:189], v[194:197], v[114:117]
	v_mfma_f32_16x16x32_bf16 v[106:109], v[178:181], v[206:209], v[106:109]
	v_mfma_f32_16x16x32_bf16 v[98:101], v[186:189], v[206:209], v[98:101]
	v_mfma_f32_16x16x32_bf16 v[90:93], v[178:181], v[214:217], v[90:93]
	v_mfma_f32_16x16x32_bf16 v[82:85], v[186:189], v[214:217], v[82:85]
	v_mfma_f32_16x16x32_bf16 v[74:77], v[178:181], v[222:225], v[74:77]
	v_mfma_f32_16x16x32_bf16 v[66:69], v[186:189], v[222:225], v[66:69]
	v_mfma_f32_16x16x32_bf16 v[122:125], v[182:185], v[202:205], v[122:125]
	v_mfma_f32_16x16x32_bf16 v[114:117], v[190:193], v[202:205], v[114:117]
	v_mfma_f32_16x16x32_bf16 v[106:109], v[182:185], v[210:213], v[106:109]
	v_mfma_f32_16x16x32_bf16 v[98:101], v[190:193], v[210:213], v[98:101]
	v_mfma_f32_16x16x32_bf16 v[90:93], v[182:185], v[218:221], v[90:93]
	v_mfma_f32_16x16x32_bf16 v[82:85], v[190:193], v[218:221], v[82:85]
	v_mfma_f32_16x16x32_bf16 v[74:77], v[182:185], v[226:229], v[74:77]
	v_mfma_f32_16x16x32_bf16 v[66:69], v[190:193], v[226:229], v[66:69]
	s_setprio 0
	s_barrier
	s_add_i32 s36, s65, s42
	s_add_u32 s26, s26, 0x80
	s_addc_u32 s27, s27, 0
	s_mov_b32 m0, s36
	ds_read_b128 v[194:197], v159 offset:49152
	ds_read_b128 v[202:205], v159 offset:50176
	ds_read_b128 v[206:209], v159 offset:51200
	ds_read_b128 v[210:213], v159 offset:52224
	ds_read_b128 v[214:217], v159 offset:53248
	ds_read_b128 v[218:221], v159 offset:54272
	ds_read_b128 v[222:225], v159 offset:55296
	ds_read_b128 v[226:229], v159 offset:56320
	global_load_lds_dwordx4 v134, s[26:27]
	s_add_i32 m0, s36, 0x2000
	s_add_i32 s36, s66, s42
	global_load_lds_dwordx4 v130, s[26:27]
	s_add_u32 s26, s26, 0x80000
	s_addc_u32 s27, s27, 0
	s_mov_b32 m0, s36
	s_nop 0
	global_load_lds_dwordx4 v134, s[26:27]
	s_add_i32 m0, s36, 0x2000
	s_nop 0
	global_load_lds_dwordx4 v130, s[26:27]
	s_waitcnt vmcnt(6)
	s_waitcnt lgkmcnt(0)
	s_barrier
	s_setprio 1
	s_waitcnt lgkmcnt(0)
	v_mfma_f32_16x16x32_bf16 v[62:65], v[162:165], v[194:197], v[62:65]
	v_mfma_f32_16x16x32_bf16 v[54:57], v[170:173], v[194:197], v[54:57]
	v_mfma_f32_16x16x32_bf16 v[46:49], v[162:165], v[206:209], v[46:49]
	v_mfma_f32_16x16x32_bf16 v[38:41], v[170:173], v[206:209], v[38:41]
	v_mfma_f32_16x16x32_bf16 v[30:33], v[162:165], v[214:217], v[30:33]
	v_mfma_f32_16x16x32_bf16 v[22:25], v[170:173], v[214:217], v[22:25]
	v_mfma_f32_16x16x32_bf16 v[14:17], v[162:165], v[222:225], v[14:17]
	v_mfma_f32_16x16x32_bf16 v[6:9], v[170:173], v[222:225], v[6:9]
	v_mfma_f32_16x16x32_bf16 v[62:65], v[166:169], v[202:205], v[62:65]
	v_mfma_f32_16x16x32_bf16 v[54:57], v[174:177], v[202:205], v[54:57]
	v_mfma_f32_16x16x32_bf16 v[46:49], v[166:169], v[210:213], v[46:49]
	v_mfma_f32_16x16x32_bf16 v[38:41], v[174:177], v[210:213], v[38:41]
	v_mfma_f32_16x16x32_bf16 v[30:33], v[166:169], v[218:221], v[30:33]
	v_mfma_f32_16x16x32_bf16 v[22:25], v[174:177], v[218:221], v[22:25]
	v_mfma_f32_16x16x32_bf16 v[14:17], v[166:169], v[226:229], v[14:17]
	v_mfma_f32_16x16x32_bf16 v[6:9], v[174:177], v[226:229], v[6:9]
	s_setprio 0
	s_setprio 1
	v_mfma_f32_16x16x32_bf16 v[58:61], v[178:181], v[194:197], v[58:61]
	v_mfma_f32_16x16x32_bf16 v[50:53], v[186:189], v[194:197], v[50:53]
	v_mfma_f32_16x16x32_bf16 v[42:45], v[178:181], v[206:209], v[42:45]
	v_mfma_f32_16x16x32_bf16 v[34:37], v[186:189], v[206:209], v[34:37]
	v_mfma_f32_16x16x32_bf16 v[26:29], v[178:181], v[214:217], v[26:29]
	v_mfma_f32_16x16x32_bf16 v[18:21], v[186:189], v[214:217], v[18:21]
	v_mfma_f32_16x16x32_bf16 v[10:13], v[178:181], v[222:225], v[10:13]
	v_mfma_f32_16x16x32_bf16 v[2:5], v[186:189], v[222:225], v[2:5]
	v_mfma_f32_16x16x32_bf16 v[58:61], v[182:185], v[202:205], v[58:61]
	v_mfma_f32_16x16x32_bf16 v[50:53], v[190:193], v[202:205], v[50:53]
	v_mfma_f32_16x16x32_bf16 v[42:45], v[182:185], v[210:213], v[42:45]
	v_mfma_f32_16x16x32_bf16 v[34:37], v[190:193], v[210:213], v[34:37]
	v_mfma_f32_16x16x32_bf16 v[26:29], v[182:185], v[218:221], v[26:29]
	v_mfma_f32_16x16x32_bf16 v[18:21], v[190:193], v[218:221], v[18:21]
	v_mfma_f32_16x16x32_bf16 v[10:13], v[182:185], v[226:229], v[10:13]
	v_mfma_f32_16x16x32_bf16 v[2:5], v[190:193], v[226:229], v[2:5]
	s_setprio 0
	s_add_i32 s64, s64, 2
	s_add_u32 s62, s62, 0x100
	s_addc_u32 s63, s63, 0
	s_add_u32 s24, s24, 0x100
	s_addc_u32 s25, s25, 0
	s_cmp_gt_u32 s64, 29
	s_barrier
	s_cbranch_scc1 .LBB0_695

; #define PG8_STAGE(bufoff, gbase, voff) do { _Pragma("unroll") for (int _i = 0; _i < 2; ++_i) \
;         __builtin_amdgcn_global_load_lds((const unsigned*)((const char*)(gbase) + (voff)[_i]), (PG8_LAS unsigned*)(lds + (bufoff) + ldsw + _i * 8192), 16, 0, 0); } while (0)
; #define PG8_LDA(dst, b, h) do { _Pragma("unroll") for (int m = 0; m < 4; ++m) _Pragma("unroll") for (int k = 0; k < 2; ++k) dst[m][k] = *(const PG8_LAS bf16x8*)(lds + PG8_SA(b, h) + aoff + m * 2048 + k * 1024); } while (0)
; #define PG8_LDB(dst, b, h) do { _Pragma("unroll") for (int n = 0; n < 2; ++n) _Pragma("unroll") for (int k = 0; k < 2; ++k) dst[n][k] = *(const PG8_LAS bf16x8*)(lds + PG8_SB(b, h) + boff + n * 2048 + k * 1024); } while (0)
; #define PG8_MMA(ai, bj, At, Bt) do { __builtin_amdgcn_s_setprio(1); _Pragma("unroll") for (int m = 0; m < 4; ++m) _Pragma("unroll") for (int n = 0; n < 2; ++n) _Pragma("unroll") for (int k = 0; k < 2; ++k) \
;         acc[ai][bj][m][n] = __builtin_amdgcn_mfma_f32_16x16x32_bf16(Bt[n][k], At[m][k], acc[ai][bj][m][n], 0, 0, 0); __builtin_amdgcn_s_setprio(0); } while (0)
; #define PG8_WAIT_V(n) asm volatile("s_waitcnt vmcnt(" #n ")" ::: "memory")
; #define PG8_BAR __builtin_amdgcn_s_barrier()
; template <class Epi, class Sched, bool ALIGN_EPI = false, bool SP2 = false>
; __device__ __forceinline__ void gemm_phase(PG8_LAS unsigned char* lds, const Gemm g, const Sched& S, const Epi& E) {
;     ...
;         for (int t = 0; t < nt; t += 2) {
;             const bool last = (t == nt - 2);
;             const char* a1 = cA + (size_t)(t + 1) * kstep;
;             const char* a2 = last ? nA : cA + (size_t)(t + 2) * kstep; const char* b2 = last ? nB : cB + (size_t)(t + 2) * kstep;
;             const char* a3 = a2 + kstep; const char* b3 = b2 + kstep;
;             if (last && has_next) S.a_ready(nxt);
;             if constexpr (SP2) {
;             PG8_LDB(B0, 0, 0); PG8_LDB(B1, 0, 1); PG8_SCHED; PG8_LDA(At, 0, 0); PG8_STAGE(PG8_SA(1, 1), a1 + hstep, voffA);
;             PG8_WAIT_V(8); PG8_WAIT_L(0); PG8_BAR; PG8_MMA(0, 0, At, B0); PG8_MMA(0, 1, At, B1); PG8_BAR; PG8_SCHED;
;             PG8_LDA(At, 0, 1); PG8_STAGE(PG8_SB(0, 0), b2, voffB); PG8_STAGE(PG8_SB(0, 1), b2 + hstep, voffB); PG8_STAGE(PG8_SA(0, 0), a2, voffA);
;             PG8_WAIT_V(8); PG8_WAIT_L(0); PG8_BAR; PG8_MMA(1, 0, At, B0); PG8_MMA(1, 1, At, B1); PG8_BAR; PG8_SCHED;
.LBB0_791:
	ds_read_b128 v[144:147], v153
	ds_read_b128 v[156:159], v153 offset:1024
	ds_read_b128 v[160:163], v153 offset:2048
	ds_read_b128 v[164:167], v153 offset:3072
	ds_read_b128 v[168:171], v154
	ds_read_b128 v[172:175], v154 offset:1024
	ds_read_b128 v[176:179], v154 offset:2048
	ds_read_b128 v[180:183], v154 offset:3072
	s_add_u32 s26, s24, 0xffea0080
	s_addc_u32 s27, s25, -1
	s_cmpk_eq_i32 s53, 0x54
	s_cselect_b32 s29, s3, s27
	s_cselect_b32 s28, s2, s26
	s_cselect_b32 s27, s23, s52
	s_cselect_b32 s26, s22, s51
	v_lshl_add_u64 v[148:149], s[24:25], 0, v[138:139]
	s_add_i32 m0, s37, 0xc000
	ds_read_b128 v[184:187], v155
	ds_read_b128 v[188:191], v155 offset:1024
	ds_read_b128 v[192:195], v155 offset:2048
	ds_read_b128 v[196:199], v155 offset:3072
	ds_read_b128 v[200:203], v155 offset:4096
	ds_read_b128 v[204:207], v155 offset:5120
	ds_read_b128 v[208:211], v155 offset:6144
	ds_read_b128 v[212:215], v155 offset:7168
	global_load_lds_dwordx4 v[148:149], off
	v_lshl_add_u64 v[148:149], s[24:25], 0, v[136:137]
	s_add_i32 m0, s37, 0xe000
	s_nop 0
	global_load_lds_dwordx4 v[148:149], off
	s_waitcnt vmcnt(8)
	s_waitcnt lgkmcnt(0)
	s_barrier
	s_setprio 1
	s_waitcnt lgkmcnt(0)
	v_mfma_f32_16x16x32_bf16 v[124:127], v[144:147], v[184:187], v[124:127]
	v_mfma_f32_16x16x32_bf16 v[120:123], v[160:163], v[184:187], v[120:123]
	v_mfma_f32_16x16x32_bf16 v[108:111], v[144:147], v[192:195], v[108:111]
	v_mfma_f32_16x16x32_bf16 v[104:107], v[160:163], v[192:195], v[104:107]
	v_mfma_f32_16x16x32_bf16 v[92:95], v[144:147], v[200:203], v[92:95]
	v_mfma_f32_16x16x32_bf16 v[88:91], v[160:163], v[200:203], v[88:91]
	v_mfma_f32_16x16x32_bf16 v[76:79], v[144:147], v[208:211], v[76:79]
	v_mfma_f32_16x16x32_bf16 v[72:75], v[160:163], v[208:211], v[72:75]
	v_mfma_f32_16x16x32_bf16 v[124:127], v[156:159], v[188:191], v[124:127]
	v_mfma_f32_16x16x32_bf16 v[120:123], v[164:167], v[188:191], v[120:123]
	v_mfma_f32_16x16x32_bf16 v[108:111], v[156:159], v[196:199], v[108:111]
	v_mfma_f32_16x16x32_bf16 v[104:107], v[164:167], v[196:199], v[104:107]
	v_mfma_f32_16x16x32_bf16 v[92:95], v[156:159], v[204:207], v[92:95]
	v_mfma_f32_16x16x32_bf16 v[88:91], v[164:167], v[204:207], v[88:91]
	v_mfma_f32_16x16x32_bf16 v[76:79], v[156:159], v[212:215], v[76:79]
	v_mfma_f32_16x16x32_bf16 v[72:75], v[164:167], v[212:215], v[72:75]
	s_setprio 0
	s_setprio 1
	v_mfma_f32_16x16x32_bf16 v[116:119], v[168:171], v[184:187], v[116:119]
	v_mfma_f32_16x16x32_bf16 v[112:115], v[176:179], v[184:187], v[112:115]
	v_mfma_f32_16x16x32_bf16 v[100:103], v[168:171], v[192:195], v[100:103]
	v_mfma_f32_16x16x32_bf16 v[96:99], v[176:179], v[192:195], v[96:99]
	v_mfma_f32_16x16x32_bf16 v[84:87], v[168:171], v[200:203], v[84:87]
	v_mfma_f32_16x16x32_bf16 v[80:83], v[176:179], v[200:203], v[80:83]
	v_mfma_f32_16x16x32_bf16 v[68:71], v[168:171], v[208:211], v[68:71]
	v_mfma_f32_16x16x32_bf16 v[64:67], v[176:179], v[208:211], v[64:67]
	v_mfma_f32_16x16x32_bf16 v[116:119], v[172:175], v[188:191], v[116:119]
	v_mfma_f32_16x16x32_bf16 v[112:115], v[180:183], v[188:191], v[112:115]
	v_mfma_f32_16x16x32_bf16 v[100:103], v[172:175], v[196:199], v[100:103]
	v_mfma_f32_16x16x32_bf16 v[96:99], v[180:183], v[196:199], v[96:99]
	v_mfma_f32_16x16x32_bf16 v[84:87], v[172:175], v[204:207], v[84:87]
	v_mfma_f32_16x16x32_bf16 v[80:83], v[180:183], v[204:207], v[80:83]
	v_mfma_f32_16x16x32_bf16 v[68:71], v[172:175], v[212:215], v[68:71]
	v_mfma_f32_16x16x32_bf16 v[64:67], v[180:183], v[212:215], v[64:67]
	s_setprio 0
	s_barrier
	s_add_i32 s54, s45, s36
	v_lshl_add_u64 v[148:149], s[26:27], 0, v[130:131]
	s_mov_b32 m0, s54
	ds_read_b128 v[184:187], v155 offset:16384
	ds_read_b128 v[188:191], v155 offset:17408
	ds_read_b128 v[192:195], v155 offset:18432
	ds_read_b128 v[196:199], v155 offset:19456
	ds_read_b128 v[200:203], v155 offset:20480
	ds_read_b128 v[204:207], v155 offset:21504
	ds_read_b128 v[208:211], v155 offset:22528
	ds_read_b128 v[212:215], v155 offset:23552
	global_load_lds_dwordx4 v[148:149], off
	s_add_i32 m0, s54, 0x2000
	s_add_u32 s54, s26, 0x160000
	v_lshl_add_u64 v[216:217], s[26:27], 0, v[134:135]
	s_addc_u32 s55, s27, 0
	s_add_i32 s56, s46, s36
	global_load_lds_dwordx4 v[216:217], off
	v_lshl_add_u64 v[218:219], s[54:55], 0, v[130:131]
	s_mov_b32 m0, s56
	v_lshl_add_u64 v[220:221], s[28:29], 0, v[132:133]
	global_load_lds_dwordx4 v[218:219], off
	v_lshl_add_u64 v[218:219], s[54:55], 0, v[134:135]
	s_add_i32 m0, s56, 0x2000
	s_nop 0
	global_load_lds_dwordx4 v[218:219], off
	v_lshl_add_u64 v[218:219], s[28:29], 0, v[128:129]
	s_mov_b32 m0, s37
	s_nop 0
	global_load_lds_dwordx4 v[218:219], off
	s_mov_b32 m0, s38
	s_nop 0
	global_load_lds_dwordx4 v[220:221], off
	s_waitcnt vmcnt(8)
	s_waitcnt lgkmcnt(0)
	s_barrier
; #define PG8_STAGE(bufoff, gbase, voff) do { _Pragma("unroll") for (int _i = 0; _i < 2; ++_i) \
;         __builtin_amdgcn_global_load_lds((const unsigned*)((const char*)(gbase) + (voff)[_i]), (PG8_LAS unsigned*)(lds + (bufoff) + ldsw + _i * 8192), 16, 0, 0); } while (0)
; #define PG8_LDA(dst, b, h) do { _Pragma("unroll") for (int m = 0; m < 4; ++m) _Pragma("unroll") for (int k = 0; k < 2; ++k) dst[m][k] = *(const PG8_LAS bf16x8*)(lds + PG8_SA(b, h) + aoff + m * 2048 + k * 1024); } while (0)
; #define PG8_LDB(dst, b, h) do { _Pragma("unroll") for (int n = 0; n < 2; ++n) _Pragma("unroll") for (int k = 0; k < 2; ++k) dst[n][k] = *(const PG8_LAS bf16x8*)(lds + PG8_SB(b, h) + boff + n * 2048 + k * 1024); } while (0)
; #define PG8_MMA(ai, bj, At, Bt) do { __builtin_amdgcn_s_setprio(1); _Pragma("unroll") for (int m = 0; m < 4; ++m) _Pragma("unroll") for (int n = 0; n < 2; ++n) _Pragma("unroll") for (int k = 0; k < 2; ++k) \
;         acc[ai][bj][m][n] = __builtin_amdgcn_mfma_f32_16x16x32_bf16(Bt[n][k], At[m][k], acc[ai][bj][m][n], 0, 0, 0); __builtin_amdgcn_s_setprio(0); } while (0)
; #define PG8_WAIT_V(n) asm volatile("s_waitcnt vmcnt(" #n ")" ::: "memory")
; #define PG8_WAIT_L(n) asm volatile("s_waitcnt lgkmcnt(" #n ")" ::: "memory")
; #define PG8_BAR __builtin_amdgcn_s_barrier()
; #define PG8_SCHED __builtin_amdgcn_sched_barrier(0)
; template <class Epi, class Sched, bool ALIGN_EPI = false, bool SP2 = false>
; __device__ __forceinline__ void gemm_phase(PG8_LAS unsigned char* lds, const Gemm g, const Sched& S, const Epi& E) {
;     ...
;             PG8_WAIT_V(8); PG8_WAIT_L(0); PG8_BAR; PG8_MMA(1, 0, At, B0); PG8_MMA(1, 1, At, B1); PG8_BAR; PG8_SCHED;
;             PG8_LDB(B0, 1, 0); PG8_LDB(B1, 1, 1); PG8_SCHED; PG8_LDA(At, 1, 0); PG8_STAGE(PG8_SA(0, 1), a2 + hstep, voffA);
;             PG8_WAIT_V(8); PG8_WAIT_L(0); PG8_BAR; PG8_MMA(0, 0, At, B0); PG8_MMA(0, 1, At, B1); PG8_BAR; PG8_SCHED;
;             PG8_LDA(At, 1, 1); PG8_STAGE(PG8_SB(1, 0), b3, voffB); PG8_STAGE(PG8_SB(1, 1), b3 + hstep, voffB); PG8_STAGE(PG8_SA(1, 0), a3, voffA);
	s_setprio 1
	s_waitcnt lgkmcnt(0)
	v_mfma_f32_16x16x32_bf16 v[60:63], v[144:147], v[184:187], v[60:63]
	v_mfma_f32_16x16x32_bf16 v[56:59], v[160:163], v[184:187], v[56:59]
	v_mfma_f32_16x16x32_bf16 v[44:47], v[144:147], v[192:195], v[44:47]
	v_mfma_f32_16x16x32_bf16 v[40:43], v[160:163], v[192:195], v[40:43]
	v_mfma_f32_16x16x32_bf16 v[28:31], v[144:147], v[200:203], v[28:31]
	v_mfma_f32_16x16x32_bf16 v[24:27], v[160:163], v[200:203], v[24:27]
	v_mfma_f32_16x16x32_bf16 v[12:15], v[144:147], v[208:211], v[12:15]
	v_mfma_f32_16x16x32_bf16 v[8:11], v[160:163], v[208:211], v[8:11]
	v_mfma_f32_16x16x32_bf16 v[60:63], v[156:159], v[188:191], v[60:63]
	v_mfma_f32_16x16x32_bf16 v[56:59], v[164:167], v[188:191], v[56:59]
	v_mfma_f32_16x16x32_bf16 v[44:47], v[156:159], v[196:199], v[44:47]
	v_mfma_f32_16x16x32_bf16 v[40:43], v[164:167], v[196:199], v[40:43]
	v_mfma_f32_16x16x32_bf16 v[28:31], v[156:159], v[204:207], v[28:31]
	v_mfma_f32_16x16x32_bf16 v[24:27], v[164:167], v[204:207], v[24:27]
	v_mfma_f32_16x16x32_bf16 v[12:15], v[156:159], v[212:215], v[12:15]
	v_mfma_f32_16x16x32_bf16 v[8:11], v[164:167], v[212:215], v[8:11]
	s_setprio 0
	s_setprio 1
	v_mfma_f32_16x16x32_bf16 v[52:55], v[168:171], v[184:187], v[52:55]
	v_mfma_f32_16x16x32_bf16 v[48:51], v[176:179], v[184:187], v[48:51]
	v_mfma_f32_16x16x32_bf16 v[36:39], v[168:171], v[192:195], v[36:39]
	v_mfma_f32_16x16x32_bf16 v[32:35], v[176:179], v[192:195], v[32:35]
	v_mfma_f32_16x16x32_bf16 v[20:23], v[168:171], v[200:203], v[20:23]
	v_mfma_f32_16x16x32_bf16 v[16:19], v[176:179], v[200:203], v[16:19]
	v_mfma_f32_16x16x32_bf16 v[4:7], v[168:171], v[208:211], v[4:7]
	v_mfma_f32_16x16x32_bf16 v[0:3], v[176:179], v[208:211], v[0:3]
	v_mfma_f32_16x16x32_bf16 v[52:55], v[172:175], v[188:191], v[52:55]
	v_mfma_f32_16x16x32_bf16 v[48:51], v[180:183], v[188:191], v[48:51]
	v_mfma_f32_16x16x32_bf16 v[36:39], v[172:175], v[196:199], v[36:39]
	v_mfma_f32_16x16x32_bf16 v[32:35], v[180:183], v[196:199], v[32:35]
	v_mfma_f32_16x16x32_bf16 v[20:23], v[172:175], v[204:207], v[20:23]
	v_mfma_f32_16x16x32_bf16 v[16:19], v[180:183], v[204:207], v[16:19]
	v_mfma_f32_16x16x32_bf16 v[4:7], v[172:175], v[212:215], v[4:7]
	v_mfma_f32_16x16x32_bf16 v[0:3], v[180:183], v[212:215], v[0:3]
	s_setprio 0
	s_barrier
	s_add_i32 s54, 0, 0x18000
	s_add_i32 s55, 0, 0x1c000
	v_add_u32_e32 v164, s54, v151
	v_add_u32_e32 v180, s55, v151
	ds_read_b128 v[144:147], v164
	ds_read_b128 v[156:159], v164 offset:1024
	ds_read_b128 v[160:163], v164 offset:2048
	ds_read_b128 v[164:167], v164 offset:3072
	ds_read_b128 v[168:171], v180
	ds_read_b128 v[172:175], v180 offset:1024
	ds_read_b128 v[176:179], v180 offset:2048
	ds_read_b128 v[180:183], v180 offset:3072
	s_add_u32 s28, s28, 0x160000
	s_addc_u32 s29, s29, 0
	s_mov_b32 m0, s39
	v_lshl_add_u64 v[222:223], s[28:29], 0, v[128:129]
	ds_read_b128 v[184:187], v155 offset:32768
	ds_read_b128 v[188:191], v155 offset:33792
	ds_read_b128 v[192:195], v155 offset:34816
	ds_read_b128 v[196:199], v155 offset:35840
	ds_read_b128 v[200:203], v155 offset:36864
	ds_read_b128 v[204:207], v155 offset:37888
	ds_read_b128 v[208:211], v155 offset:38912
	ds_read_b128 v[212:215], v155 offset:39936
	global_load_lds_dwordx4 v[222:223], off
	v_lshl_add_u64 v[222:223], s[28:29], 0, v[132:133]
	s_mov_b32 m0, s40
	s_nop 0
	global_load_lds_dwordx4 v[222:223], off
	s_waitcnt vmcnt(8)
	s_waitcnt lgkmcnt(0)
	s_barrier
	s_setprio 1
	s_waitcnt lgkmcnt(0)
	v_mfma_f32_16x16x32_bf16 v[124:127], v[144:147], v[184:187], v[124:127]
	v_mfma_f32_16x16x32_bf16 v[120:123], v[160:163], v[184:187], v[120:123]
	v_mfma_f32_16x16x32_bf16 v[108:111], v[144:147], v[192:195], v[108:111]
	v_mfma_f32_16x16x32_bf16 v[104:107], v[160:163], v[192:195], v[104:107]
	v_mfma_f32_16x16x32_bf16 v[92:95], v[144:147], v[200:203], v[92:95]
	v_mfma_f32_16x16x32_bf16 v[88:91], v[160:163], v[200:203], v[88:91]
	v_mfma_f32_16x16x32_bf16 v[76:79], v[144:147], v[208:211], v[76:79]
	v_mfma_f32_16x16x32_bf16 v[72:75], v[160:163], v[208:211], v[72:75]
	v_mfma_f32_16x16x32_bf16 v[124:127], v[156:159], v[188:191], v[124:127]
	v_mfma_f32_16x16x32_bf16 v[120:123], v[164:167], v[188:191], v[120:123]
	v_mfma_f32_16x16x32_bf16 v[108:111], v[156:159], v[196:199], v[108:111]
	v_mfma_f32_16x16x32_bf16 v[104:107], v[164:167], v[196:199], v[104:107]
	v_mfma_f32_16x16x32_bf16 v[92:95], v[156:159], v[204:207], v[92:95]
	v_mfma_f32_16x16x32_bf16 v[88:91], v[164:167], v[204:207], v[88:91]
	v_mfma_f32_16x16x32_bf16 v[76:79], v[156:159], v[212:215], v[76:79]
	v_mfma_f32_16x16x32_bf16 v[72:75], v[164:167], v[212:215], v[72:75]
	s_setprio 0
	s_setprio 1
	v_mfma_f32_16x16x32_bf16 v[116:119], v[168:171], v[184:187], v[116:119]
	v_mfma_f32_16x16x32_bf16 v[112:115], v[176:179], v[184:187], v[112:115]
	v_mfma_f32_16x16x32_bf16 v[100:103], v[168:171], v[192:195], v[100:103]
	v_mfma_f32_16x16x32_bf16 v[96:99], v[176:179], v[192:195], v[96:99]
	v_mfma_f32_16x16x32_bf16 v[84:87], v[168:171], v[200:203], v[84:87]
	v_mfma_f32_16x16x32_bf16 v[80:83], v[176:179], v[200:203], v[80:83]
	v_mfma_f32_16x16x32_bf16 v[68:71], v[168:171], v[208:211], v[68:71]
	v_mfma_f32_16x16x32_bf16 v[64:67], v[176:179], v[208:211], v[64:67]
	v_mfma_f32_16x16x32_bf16 v[116:119], v[172:175], v[188:191], v[116:119]
	v_mfma_f32_16x16x32_bf16 v[112:115], v[180:183], v[188:191], v[112:115]
	v_mfma_f32_16x16x32_bf16 v[100:103], v[172:175], v[196:199], v[100:103]
	v_mfma_f32_16x16x32_bf16 v[96:99], v[180:183], v[196:199], v[96:99]
	v_mfma_f32_16x16x32_bf16 v[84:87], v[172:175], v[204:207], v[84:87]
	v_mfma_f32_16x16x32_bf16 v[80:83], v[180:183], v[204:207], v[80:83]
	v_mfma_f32_16x16x32_bf16 v[68:71], v[172:175], v[212:215], v[68:71]
	v_mfma_f32_16x16x32_bf16 v[64:67], v[180:183], v[212:215], v[64:67]
	s_setprio 0
	s_barrier
; #define PG8_STAGE(bufoff, gbase, voff) do { _Pragma("unroll") for (int _i = 0; _i < 2; ++_i) \
;         __builtin_amdgcn_global_load_lds((const unsigned*)((const char*)(gbase) + (voff)[_i]), (PG8_LAS unsigned*)(lds + (bufoff) + ldsw + _i * 8192), 16, 0, 0); } while (0)
; #define PG8_LDA(dst, b, h) do { _Pragma("unroll") for (int m = 0; m < 4; ++m) _Pragma("unroll") for (int k = 0; k < 2; ++k) dst[m][k] = *(const PG8_LAS bf16x8*)(lds + PG8_SA(b, h) + aoff + m * 2048 + k * 1024); } while (0)
; #define PG8_MMA(ai, bj, At, Bt) do { __builtin_amdgcn_s_setprio(1); _Pragma("unroll") for (int m = 0; m < 4; ++m) _Pragma("unroll") for (int n = 0; n < 2; ++n) _Pragma("unroll") for (int k = 0; k < 2; ++k) \
;         acc[ai][bj][m][n] = __builtin_amdgcn_mfma_f32_16x16x32_bf16(Bt[n][k], At[m][k], acc[ai][bj][m][n], 0, 0, 0); __builtin_amdgcn_s_setprio(0); } while (0)
; #define PG8_WAIT_V(n) asm volatile("s_waitcnt vmcnt(" #n ")" ::: "memory")
; #define PG8_WAIT_L(n) asm volatile("s_waitcnt lgkmcnt(" #n ")" ::: "memory")
; #define PG8_BAR __builtin_amdgcn_s_barrier()
; #define PG8_SCHED __builtin_amdgcn_sched_barrier(0)
; template <class Epi, class Sched, bool ALIGN_EPI = false, bool SP2 = false>
; __device__ __forceinline__ void gemm_phase(PG8_LAS unsigned char* lds, const Gemm g, const Sched& S, const Epi& E) {
;     ...
;             PG8_LDA(At, 1, 1); PG8_STAGE(PG8_SB(1, 0), b3, voffB); PG8_STAGE(PG8_SB(1, 1), b3 + hstep, voffB); PG8_STAGE(PG8_SA(1, 0), a3, voffA);
;             PG8_WAIT_V(8); PG8_WAIT_L(0); PG8_BAR; PG8_MMA(1, 0, At, B0); PG8_MMA(1, 1, At, B1); PG8_BAR; PG8_SCHED;
;     ...
;         if constexpr (ALIGN_EPI) { if (wr == 0) PG8_BAR; }
	s_add_i32 s28, s54, s36
	v_lshl_add_u64 v[148:149], v[148:149], 0, s[8:9]
	s_mov_b32 m0, s28
	ds_read_b128 v[184:187], v155 offset:49152
	ds_read_b128 v[188:191], v155 offset:50176
	ds_read_b128 v[192:195], v155 offset:51200
	ds_read_b128 v[196:199], v155 offset:52224
	ds_read_b128 v[200:203], v155 offset:53248
	ds_read_b128 v[204:207], v155 offset:54272
	ds_read_b128 v[208:211], v155 offset:55296
	ds_read_b128 v[212:215], v155 offset:56320
	global_load_lds_dwordx4 v[148:149], off
	s_add_i32 m0, s28, 0x2000
	s_add_u32 s26, s26, 0x160080
	v_lshl_add_u64 v[148:149], v[216:217], 0, s[8:9]
	s_addc_u32 s27, s27, 0
	s_add_i32 s28, s55, s36
	global_load_lds_dwordx4 v[148:149], off
	v_lshl_add_u64 v[148:149], s[26:27], 0, v[130:131]
	s_mov_b32 m0, s28
	s_nop 0
	global_load_lds_dwordx4 v[148:149], off
	v_lshl_add_u64 v[148:149], s[26:27], 0, v[134:135]
	s_add_i32 m0, s28, 0x2000
	s_nop 0
	global_load_lds_dwordx4 v[148:149], off
	v_lshl_add_u64 v[148:149], v[218:219], 0, s[8:9]
	s_mov_b32 m0, s42
	s_nop 0
	global_load_lds_dwordx4 v[148:149], off
	v_lshl_add_u64 v[148:149], v[220:221], 0, s[8:9]
	s_mov_b32 m0, s43
	s_nop 0
	global_load_lds_dwordx4 v[148:149], off
	s_waitcnt vmcnt(8)
	s_waitcnt lgkmcnt(0)
	s_barrier
	s_setprio 1
	s_waitcnt lgkmcnt(0)
	v_mfma_f32_16x16x32_bf16 v[60:63], v[144:147], v[184:187], v[60:63]
	v_mfma_f32_16x16x32_bf16 v[56:59], v[160:163], v[184:187], v[56:59]
	v_mfma_f32_16x16x32_bf16 v[44:47], v[144:147], v[192:195], v[44:47]
	v_mfma_f32_16x16x32_bf16 v[40:43], v[160:163], v[192:195], v[40:43]
	v_mfma_f32_16x16x32_bf16 v[28:31], v[144:147], v[200:203], v[28:31]
	v_mfma_f32_16x16x32_bf16 v[24:27], v[160:163], v[200:203], v[24:27]
	v_mfma_f32_16x16x32_bf16 v[12:15], v[144:147], v[208:211], v[12:15]
	v_mfma_f32_16x16x32_bf16 v[8:11], v[160:163], v[208:211], v[8:11]
	v_mfma_f32_16x16x32_bf16 v[60:63], v[156:159], v[188:191], v[60:63]
	v_mfma_f32_16x16x32_bf16 v[56:59], v[164:167], v[188:191], v[56:59]
	v_mfma_f32_16x16x32_bf16 v[44:47], v[156:159], v[196:199], v[44:47]
	v_mfma_f32_16x16x32_bf16 v[40:43], v[164:167], v[196:199], v[40:43]
	v_mfma_f32_16x16x32_bf16 v[28:31], v[156:159], v[204:207], v[28:31]
	v_mfma_f32_16x16x32_bf16 v[24:27], v[164:167], v[204:207], v[24:27]
	v_mfma_f32_16x16x32_bf16 v[12:15], v[156:159], v[212:215], v[12:15]
	v_mfma_f32_16x16x32_bf16 v[8:11], v[164:167], v[212:215], v[8:11]
	s_setprio 0
	s_setprio 1
	v_mfma_f32_16x16x32_bf16 v[52:55], v[168:171], v[184:187], v[52:55]
	v_mfma_f32_16x16x32_bf16 v[48:51], v[176:179], v[184:187], v[48:51]
	v_mfma_f32_16x16x32_bf16 v[36:39], v[168:171], v[192:195], v[36:39]
	v_mfma_f32_16x16x32_bf16 v[32:35], v[176:179], v[192:195], v[32:35]
	v_mfma_f32_16x16x32_bf16 v[20:23], v[168:171], v[200:203], v[20:23]
	v_mfma_f32_16x16x32_bf16 v[16:19], v[176:179], v[200:203], v[16:19]
	v_mfma_f32_16x16x32_bf16 v[4:7], v[168:171], v[208:211], v[4:7]
	v_mfma_f32_16x16x32_bf16 v[0:3], v[176:179], v[208:211], v[0:3]
	v_mfma_f32_16x16x32_bf16 v[52:55], v[172:175], v[188:191], v[52:55]
	v_mfma_f32_16x16x32_bf16 v[48:51], v[180:183], v[188:191], v[48:51]
	v_mfma_f32_16x16x32_bf16 v[36:39], v[172:175], v[196:199], v[36:39]
	v_mfma_f32_16x16x32_bf16 v[32:35], v[180:183], v[196:199], v[32:35]
	v_mfma_f32_16x16x32_bf16 v[20:23], v[172:175], v[204:207], v[20:23]
	v_mfma_f32_16x16x32_bf16 v[16:19], v[180:183], v[204:207], v[16:19]
	v_mfma_f32_16x16x32_bf16 v[4:7], v[172:175], v[212:215], v[4:7]
	v_mfma_f32_16x16x32_bf16 v[0:3], v[180:183], v[212:215], v[0:3]
	s_setprio 0
	s_add_i32 s53, s53, 2
	s_add_u32 s51, s51, 0x100
	s_addc_u32 s52, s52, 0
	s_add_u32 s24, s24, 0x100
	s_addc_u32 s25, s25, 0
	s_cmpk_gt_u32 s53, 0x55
	s_barrier
	s_cbranch_scc0 .LBB0_791
	s_and_b64 vcc, exec, s[12:13]
	s_cbranch_vccz .LBB0_794
	s_barrier
